# baseline (speedup 1.0000x reference)
; __device__ __forceinline__ u32x2 pack4(float a, float b, float c, float d) { return u32x2{cvtpk(a, b), cvtpk(c, d)}; }
; __device__ __forceinline__ u32x2 pack4(const f32x4& v) { return u32x2{cvtpk(v[0], v[1]), cvtpk(v[2], v[3])}; }
; #define SBAR() __builtin_amdgcn_sched_barrier(0)
; __global__ void __launch_bounds__(512) fwd_megakernel(Params p) {
;     ...
;         for (int ai = 0; ai < 2; ++ai)
;           #pragma unroll
;           for (int mp = 0; mp < 2; ++mp) { SBAR();
;             f32x4 xv[2][2][2];
;             #pragma unroll
;             for (int mm = 0; mm < 2; ++mm) {
;               const float* xr = xrow_ptr(p, brow + ai * 128 + wr * 64 + (mp * 2 + mm) * 16 + fr) + pn * 256 + wc * 32 + fq * 4;
;               #pragma unroll
;               for (int bj = 0; bj < 2; ++bj)
;                 #pragma unroll
;                 for (int n = 0; n < 2; ++n) xv[mm][bj][n] = *reinterpret_cast<const f32x4*>(xr + bj * 128 + n * 16);
;             }
;             SBAR();
;             #pragma unroll
;             for (int mm = 0; mm < 2; ++mm) {
;               const int m = mp * 2 + mm;
;               int lrow = ai * 128 + wr * 64 + m * 16 + fr, row = brow + lrow; float ss = 0.f;
;               bf16* hd = p_h1b + (long)row * DM + pn * 256 + wc * 32 + fq * 4;
;               #pragma unroll
;               for (int bj = 0; bj < 2; ++bj)
;                 #pragma unroll
;                 for (int n = 0; n < 2; ++n) {
;                   f32x4 v = acc[ai][bj][m][n] + xv[mm][bj][n];
;                   ss += (v[0] * v[0] + v[1] * v[1]) + (v[2] * v[2] + v[3] * v[3]);
;                   *reinterpret_cast<u32x2*>(hd + bj * 128 + n * 16) = pack4(v);
;                 }
;               ss += __shfl_xor(ss, 16); ss += __shfl_xor(ss, 32);
;               if (fq == 0) red[wc * 256 + lrow] = ss;
.LBB0_605:
	v_mov_b32_e32 v128, v252
	s_waitcnt lgkmcnt(0)
	s_barrier
	s_nop 0
	v_bfe_u32 v152, v128, 6, 2
	v_and_b32_e32 v129, 15, v128
	v_bfe_u32 v153, v128, 4, 2
	v_ashrrev_i32_e32 v128, 2, v128
	v_and_or_b32 v151, v128, s63, v129
	v_cmp_eq_u32_e32 vcc, 0, v153
	v_lshl_add_u32 v172, v152, 10, s69
	v_add_u32_e32 v148, s40, v151
	v_add_u32_e32 v128, 0xffff8000, v148
	v_ashrrev_i32_e32 v149, 31, v148
	v_cmp_gt_i32_e64 s[0:1], s60, v148
	v_mov_b32_e32 v132, s39
	v_mov_b32_e32 v133, s37
	v_cndmask_b32_e64 v129, 0, v149, s[0:1]
	v_cndmask_b32_e64 v128, v128, v148, s[0:1]
	v_mov_b32_e32 v134, s38
	v_mov_b32_e32 v135, s36
	s_ashr_i32 s43, s42, 31
	v_cndmask_b32_e64 v131, v132, v133, s[0:1]
	v_cndmask_b32_e64 v130, v134, v135, s[0:1]
	v_lshlrev_b64 v[128:129], 12, v[128:129]
	v_lshl_add_u64 v[128:129], v[130:131], 0, v[128:129]
	s_lshl_b64 s[44:45], s[42:43], 2
	v_lshl_add_u64 v[128:129], v[128:129], 0, s[44:45]
	v_lshlrev_b32_e32 v146, 7, v152
	v_lshl_add_u64 v[128:129], v[128:129], 0, v[146:147]
	v_lshlrev_b32_e32 v130, 4, v153
	v_mov_b32_e32 v131, v147
	v_lshl_add_u64 v[128:129], v[128:129], 0, v[130:131]
	global_load_dwordx4 v[154:157], v[128:129], off
	global_load_dwordx4 v[158:161], v[128:129], off offset:64
	global_load_dwordx4 v[162:165], v[128:129], off offset:512
	global_load_dwordx4 v[166:169], v[128:129], off offset:576
	v_or_b32_e32 v128, 16, v148
	v_add_u32_e32 v136, 0xffff8010, v148
	v_ashrrev_i32_e32 v129, 31, v128
	v_cmp_gt_i32_e64 s[0:1], s60, v128
	s_nop 1
	v_cndmask_b32_e64 v129, 0, v129, s[0:1]
	v_cndmask_b32_e64 v128, v136, v128, s[0:1]
	v_cndmask_b32_e64 v133, v132, v133, s[0:1]
	v_cndmask_b32_e64 v132, v134, v135, s[0:1]
	v_lshlrev_b64 v[128:129], 12, v[128:129]
	v_lshl_add_u64 v[128:129], v[132:133], 0, v[128:129]
	v_lshl_add_u64 v[128:129], v[128:129], 0, s[44:45]
	v_lshl_add_u64 v[128:129], v[128:129], 0, v[146:147]
	v_lshl_add_u64 v[128:129], v[128:129], 0, v[130:131]
	global_load_dwordx4 v[140:143], v[128:129], off
	global_load_dwordx4 v[136:139], v[128:129], off offset:64
	global_load_dwordx4 v[132:135], v[128:129], off offset:512
	s_nop 0
	global_load_dwordx4 v[128:131], v[128:129], off offset:576
	v_lshlrev_b64 v[170:171], 11, v[148:149]
	v_lshl_add_u64 v[170:171], s[26:27], 0, v[170:171]
	v_lshl_add_u64 v[170:171], s[42:43], 1, v[170:171]
	v_lshlrev_b32_e32 v146, 6, v152
	v_lshl_add_u64 v[170:171], v[170:171], 0, v[146:147]
	v_lshlrev_b32_e32 v146, 3, v153
	s_waitcnt vmcnt(0)
	v_pk_add_f32 v[124:125], v[124:125], v[154:155]
	v_lshl_add_u64 v[170:171], v[170:171], 0, v[146:147]
	v_mul_f32_e32 v146, v125, v125
	v_pk_add_f32 v[126:127], v[126:127], v[156:157]
	v_fmac_f32_e32 v146, v124, v124
	v_cvt_pk_bf16_f32 v124, v124, v125
	v_cvt_pk_bf16_f32 v125, v126, v127
	v_pk_add_f32 v[118:119], v[118:119], v[160:161]
	v_pk_add_f32 v[116:117], v[116:117], v[158:159]
	v_mul_f32_e32 v149, v127, v127
	v_mov_b32_e32 v196, v124
	v_mov_b32_e32 v197, v125
	v_mul_f32_e32 v124, v117, v117
	v_mul_f32_e32 v125, v119, v119
	v_pk_add_f32 v[122:123], v[122:123], v[164:165]
	v_pk_add_f32 v[120:121], v[120:121], v[162:163]
	v_fmac_f32_e32 v149, v126, v126
	v_fmac_f32_e32 v124, v116, v116
	v_fmac_f32_e32 v125, v118, v118
	v_cvt_pk_bf16_f32 v116, v116, v117
	v_cvt_pk_bf16_f32 v117, v118, v119
	v_mul_f32_e32 v118, v121, v121
	v_mul_f32_e32 v119, v123, v123
	v_add_f32_e32 v146, v146, v149
	v_add_f32_e32 v124, v124, v125
	v_fmac_f32_e32 v118, v120, v120
	v_fmac_f32_e32 v119, v122, v122
	v_add_f32_e32 v124, v146, v124
	v_add_f32_e32 v118, v118, v119
	v_add_f32_e32 v118, v124, v118
	v_pk_add_f32 v[114:115], v[114:115], v[168:169]
	v_pk_add_f32 v[124:125], v[112:113], v[166:167]
	v_mul_f32_e32 v113, v115, v115
	v_mul_f32_e32 v112, v125, v125
	v_fmac_f32_e32 v112, v124, v124
	v_fmac_f32_e32 v113, v114, v114
	v_add_f32_e32 v112, v112, v113
	v_and_b32_e32 v113, 64, v145
	v_add_f32_e32 v118, v118, v112
	v_xor_b32_e32 v112, 16, v145
	v_add_u32_e32 v126, 64, v113
	v_cmp_lt_i32_e64 s[0:1], v112, v126
	v_mov_b32_e32 v198, v116
	v_mov_b32_e32 v199, v117
	v_bfe_u32 v194, v252, 4, 1
	v_mul_u32_u24_e32 v194, 24, v194
	v_mov_b32_e32 v195, 0
	v_lshl_add_u64 v[200:201], v[170:171], 0, v[194:195]
	v_permlane16_swap_b32_e32 v196, v198
	v_permlane16_swap_b32_e32 v197, v199
	global_store_dwordx4 v[200:201], v[196:199], off
	s_nop 1
	s_nop 0
	v_cndmask_b32_e64 v112, v145, v112, s[0:1]
	v_lshlrev_b32_e32 v119, 2, v112
	v_mov_b32_e32 v127, v118
	s_nop 1
	v_permlane16_swap_b32_e32 v118, v127
	v_cvt_pk_bf16_f32 v112, v120, v121
	v_cvt_pk_bf16_f32 v113, v122, v123
	v_mov_b32_e32 v196, v112
	v_mov_b32_e32 v197, v113
	v_xor_b32_e32 v113, 32, v145
	v_cmp_lt_i32_e64 s[0:1], v113, v126
	s_waitcnt lgkmcnt(0)
	v_add_f32_e32 v112, v118, v127
	v_lshl_add_u32 v118, v151, 2, v172
	v_cndmask_b32_e64 v113, v145, v113, s[0:1]
	v_lshlrev_b32_e32 v120, 2, v113
	v_mov_b32_e32 v113, v112
	s_nop 1
	v_permlane32_swap_b32_e32 v112, v113
	v_cvt_pk_bf16_f32 v116, v124, v125
	v_cvt_pk_bf16_f32 v117, v114, v115
	v_mov_b32_e32 v198, v116
	v_mov_b32_e32 v199, v117
	v_bfe_u32 v194, v252, 4, 1
	v_mul_u32_u24_e32 v194, 24, v194
	v_mov_b32_e32 v195, 0
	v_lshl_add_u64 v[200:201], v[170:171], 0, v[194:195]
	v_permlane16_swap_b32_e32 v196, v198
	v_permlane16_swap_b32_e32 v197, v199
	global_store_dwordx4 v[200:201], v[196:199], off offset:256
	s_nop 1
	s_and_saveexec_b64 s[0:1], vcc
	s_cbranch_execz .LBB0_607
	s_waitcnt lgkmcnt(0)
	v_add_f32_e32 v112, v112, v113
	ds_write_b32 v118, v112
; __device__ __forceinline__ u32x2 pack4(float a, float b, float c, float d) { return u32x2{cvtpk(a, b), cvtpk(c, d)}; }
; __device__ __forceinline__ u32x2 pack4(const f32x4& v) { return u32x2{cvtpk(v[0], v[1]), cvtpk(v[2], v[3])}; }
; #define SBAR() __builtin_amdgcn_sched_barrier(0)
; __global__ void __launch_bounds__(512) fwd_megakernel(Params p) {
;     ...
;         for (int ai = 0; ai < 2; ++ai)
;           #pragma unroll
;           for (int mp = 0; mp < 2; ++mp) { SBAR();
;             f32x4 xv[2][2][2];
;             #pragma unroll
;             for (int mm = 0; mm < 2; ++mm) {
;               const float* xr = xrow_ptr(p, brow + ai * 128 + wr * 64 + (mp * 2 + mm) * 16 + fr) + pn * 256 + wc * 32 + fq * 4;
;               #pragma unroll
;               for (int bj = 0; bj < 2; ++bj)
;                 #pragma unroll
;                 for (int n = 0; n < 2; ++n) xv[mm][bj][n] = *reinterpret_cast<const f32x4*>(xr + bj * 128 + n * 16);
;             }
;             SBAR();
;             #pragma unroll
;             for (int mm = 0; mm < 2; ++mm) {
;               const int m = mp * 2 + mm;
;               int lrow = ai * 128 + wr * 64 + m * 16 + fr, row = brow + lrow; float ss = 0.f;
;               bf16* hd = p_h1b + (long)row * DM + pn * 256 + wc * 32 + fq * 4;
;               #pragma unroll
;               for (int bj = 0; bj < 2; ++bj)
;                 #pragma unroll
;                 for (int n = 0; n < 2; ++n) {
;                   f32x4 v = acc[ai][bj][m][n] + xv[mm][bj][n];
;                   ss += (v[0] * v[0] + v[1] * v[1]) + (v[2] * v[2] + v[3] * v[3]);
;                   *reinterpret_cast<u32x2*>(hd + bj * 128 + n * 16) = pack4(v);
;                 }
;               ss += __shfl_xor(ss, 16); ss += __shfl_xor(ss, 32);
;               if (fq == 0) red[wc * 256 + lrow] = ss;
.LBB0_607:
	s_or_b64 exec, exec, s[0:1]
	v_add3_u32 v112, s40, v151, 16
	s_waitcnt lgkmcnt(0)
	v_ashrrev_i32_e32 v113, 31, v112
	v_lshlrev_b64 v[112:113], 11, v[112:113]
	v_lshlrev_b32_e32 v114, 5, v152
	v_lshl_add_u64 v[112:113], s[26:27], 0, v[112:113]
	v_lshlrev_b32_e32 v116, 2, v153
	v_lshl_add_u64 v[112:113], s[42:43], 1, v[112:113]
	v_lshlrev_b32_e32 v146, 1, v114
	v_pk_add_f32 v[108:109], v[108:109], v[140:141]
	v_lshl_add_u64 v[122:123], v[112:113], 0, v[146:147]
	v_lshlrev_b32_e32 v112, 1, v116
	v_mov_b32_e32 v113, v147
	v_mul_f32_e32 v115, v109, v109
	v_lshl_add_u64 v[122:123], v[122:123], 0, v[112:113]
	v_pk_add_f32 v[110:111], v[110:111], v[142:143]
	v_fmac_f32_e32 v115, v108, v108
	v_cvt_pk_bf16_f32 v108, v108, v109
	v_cvt_pk_bf16_f32 v109, v110, v111
	v_pk_add_f32 v[102:103], v[102:103], v[138:139]
	v_pk_add_f32 v[100:101], v[100:101], v[136:137]
	v_mov_b32_e32 v196, v108
	v_mov_b32_e32 v197, v109
	v_mul_f32_e32 v108, v101, v101
	v_mul_f32_e32 v109, v103, v103
	v_mul_f32_e32 v117, v111, v111
	v_fmac_f32_e32 v108, v100, v100
	v_fmac_f32_e32 v109, v102, v102
	v_pk_add_f32 v[106:107], v[106:107], v[134:135]
	v_pk_add_f32 v[104:105], v[104:105], v[132:133]
	v_fmac_f32_e32 v117, v110, v110
	v_add_f32_e32 v108, v108, v109
	v_cvt_pk_bf16_f32 v100, v100, v101
	v_mul_f32_e32 v101, v105, v105
	v_mul_f32_e32 v109, v107, v107
	v_add_f32_e32 v115, v115, v117
	v_fmac_f32_e32 v101, v104, v104
	v_fmac_f32_e32 v109, v106, v106
	v_add_f32_e32 v108, v115, v108
	v_add_f32_e32 v101, v101, v109
	v_add_f32_e32 v101, v108, v101
	v_pk_add_f32 v[98:99], v[98:99], v[130:131]
	v_pk_add_f32 v[108:109], v[96:97], v[128:129]
	v_mul_f32_e32 v97, v99, v99
	v_mul_f32_e32 v96, v109, v109
	v_fmac_f32_e32 v96, v108, v108
	v_fmac_f32_e32 v97, v98, v98
	v_add_f32_e32 v96, v96, v97
	v_add_f32_e32 v96, v101, v96
	v_mov_b32_e32 v97, v96
	s_nop 1
	v_permlane16_swap_b32_e32 v96, v97
	v_cvt_pk_bf16_f32 v101, v102, v103
	v_mov_b32_e32 v198, v100
	v_mov_b32_e32 v199, v101
	v_bfe_u32 v194, v252, 4, 1
	v_mul_u32_u24_e32 v194, 24, v194
	v_mov_b32_e32 v195, 0
	v_lshl_add_u64 v[200:201], v[122:123], 0, v[194:195]
	v_permlane16_swap_b32_e32 v196, v198
	v_permlane16_swap_b32_e32 v197, v199
	global_store_dwordx4 v[200:201], v[196:199], off
	s_nop 1
	v_cvt_pk_bf16_f32 v100, v104, v105
	v_cvt_pk_bf16_f32 v101, v106, v107
	s_waitcnt lgkmcnt(0)
	v_add_f32_e32 v96, v96, v97
	v_mov_b32_e32 v97, v96
	s_nop 1
	v_permlane32_swap_b32_e32 v96, v97
	v_mov_b32_e32 v196, v100
	v_mov_b32_e32 v197, v101
	v_cvt_pk_bf16_f32 v100, v108, v109
	v_cvt_pk_bf16_f32 v101, v98, v99
	v_mov_b32_e32 v198, v100
	v_mov_b32_e32 v199, v101
	v_bfe_u32 v194, v252, 4, 1
	v_mul_u32_u24_e32 v194, 24, v194
	v_mov_b32_e32 v195, 0
	v_lshl_add_u64 v[200:201], v[122:123], 0, v[194:195]
	v_permlane16_swap_b32_e32 v196, v198
	v_permlane16_swap_b32_e32 v197, v199
	global_store_dwordx4 v[200:201], v[196:199], off offset:256
	s_nop 1
	s_and_saveexec_b64 s[0:1], vcc
	s_cbranch_execz .LBB0_609
	s_waitcnt lgkmcnt(0)
	v_add_f32_e32 v96, v96, v97
	ds_write_b32 v118, v96 offset:64
.LBB0_609:
	s_or_b64 exec, exec, s[0:1]
	v_add_u32_e32 v138, 32, v148
	v_add_u32_e32 v96, 0xffff8020, v148
	v_ashrrev_i32_e32 v139, 31, v138
	v_cmp_gt_i32_e64 s[0:1], s60, v138
	v_mov_b32_e32 v100, s39
	v_mov_b32_e32 v101, s37
	s_waitcnt lgkmcnt(0)
	v_cndmask_b32_e64 v97, 0, v139, s[0:1]
	v_cndmask_b32_e64 v96, v96, v138, s[0:1]
	v_mov_b32_e32 v102, s38
	v_mov_b32_e32 v103, s36
	v_cndmask_b32_e64 v99, v100, v101, s[0:1]
	v_cndmask_b32_e64 v98, v102, v103, s[0:1]
	v_lshlrev_b64 v[96:97], 12, v[96:97]
	v_lshl_add_u64 v[96:97], v[98:99], 0, v[96:97]
	v_lshl_add_u64 v[96:97], v[96:97], 0, s[44:45]
	v_lshlrev_b32_e32 v114, 2, v114
	v_mov_b32_e32 v115, v147
	v_lshl_add_u64 v[96:97], v[96:97], 0, v[114:115]
	v_lshlrev_b32_e32 v116, 2, v116
	v_mov_b32_e32 v117, v147
	v_lshl_add_u64 v[96:97], v[96:97], 0, v[116:117]
	global_load_dwordx4 v[122:125], v[96:97], off
	global_load_dwordx4 v[126:129], v[96:97], off offset:64
	global_load_dwordx4 v[130:133], v[96:97], off offset:512
	global_load_dwordx4 v[134:137], v[96:97], off offset:576
	v_add_u32_e32 v96, 48, v148
	v_add_u32_e32 v98, 0xffff8030, v148
	v_ashrrev_i32_e32 v97, 31, v96
	v_cmp_gt_i32_e64 s[0:1], s60, v96
	s_nop 1
	v_cndmask_b32_e64 v97, 0, v97, s[0:1]
	v_cndmask_b32_e64 v96, v98, v96, s[0:1]
	v_cndmask_b32_e64 v99, v100, v101, s[0:1]
	v_cndmask_b32_e64 v98, v102, v103, s[0:1]
	v_lshlrev_b64 v[96:97], 12, v[96:97]
	v_lshl_add_u64 v[96:97], v[98:99], 0, v[96:97]
	v_lshl_add_u64 v[96:97], v[96:97], 0, s[44:45]
	v_lshl_add_u64 v[96:97], v[96:97], 0, v[114:115]
	v_lshl_add_u64 v[96:97], v[96:97], 0, v[116:117]
	global_load_dwordx4 v[108:111], v[96:97], off
	global_load_dwordx4 v[104:107], v[96:97], off offset:64
	global_load_dwordx4 v[100:103], v[96:97], off offset:512
	s_nop 0
	global_load_dwordx4 v[96:99], v[96:97], off offset:576
	v_lshlrev_b64 v[138:139], 11, v[138:139]
	v_lshl_add_u64 v[138:139], s[26:27], 0, v[138:139]
	v_lshl_add_u64 v[138:139], s[42:43], 1, v[138:139]
	v_lshl_add_u64 v[138:139], v[138:139], 0, v[146:147]
	s_waitcnt vmcnt(7)
	v_pk_add_f32 v[92:93], v[92:93], v[122:123]
	v_lshl_add_u64 v[138:139], v[138:139], 0, v[112:113]
	v_mul_f32_e32 v113, v93, v93
	v_pk_add_f32 v[94:95], v[94:95], v[124:125]
	v_fmac_f32_e32 v113, v92, v92
	v_cvt_pk_bf16_f32 v92, v92, v93
	v_cvt_pk_bf16_f32 v93, v94, v95
	s_waitcnt vmcnt(6)
	v_pk_add_f32 v[86:87], v[86:87], v[128:129]
	v_pk_add_f32 v[84:85], v[84:85], v[126:127]
	v_mov_b32_e32 v196, v92
	v_mov_b32_e32 v197, v93
	v_mul_f32_e32 v92, v85, v85
	v_mul_f32_e32 v93, v87, v87
	v_mul_f32_e32 v115, v95, v95
	v_fmac_f32_e32 v92, v84, v84
	v_fmac_f32_e32 v93, v86, v86
	s_waitcnt vmcnt(5)
; __device__ __forceinline__ u32x2 pack4(float a, float b, float c, float d) { return u32x2{cvtpk(a, b), cvtpk(c, d)}; }
; __device__ __forceinline__ u32x2 pack4(const f32x4& v) { return u32x2{cvtpk(v[0], v[1]), cvtpk(v[2], v[3])}; }
; #define SBAR() __builtin_amdgcn_sched_barrier(0)
; __global__ void __launch_bounds__(512) fwd_megakernel(Params p) {
;     ...
;         for (int ai = 0; ai < 2; ++ai)
;           #pragma unroll
;           for (int mp = 0; mp < 2; ++mp) { SBAR();
;             f32x4 xv[2][2][2];
;             #pragma unroll
;             for (int mm = 0; mm < 2; ++mm) {
;               const float* xr = xrow_ptr(p, brow + ai * 128 + wr * 64 + (mp * 2 + mm) * 16 + fr) + pn * 256 + wc * 32 + fq * 4;
;               #pragma unroll
;               for (int bj = 0; bj < 2; ++bj)
;                 #pragma unroll
;                 for (int n = 0; n < 2; ++n) xv[mm][bj][n] = *reinterpret_cast<const f32x4*>(xr + bj * 128 + n * 16);
;             }
;             SBAR();
;             #pragma unroll
;             for (int mm = 0; mm < 2; ++mm) {
;               const int m = mp * 2 + mm;
;               int lrow = ai * 128 + wr * 64 + m * 16 + fr, row = brow + lrow; float ss = 0.f;
;               bf16* hd = p_h1b + (long)row * DM + pn * 256 + wc * 32 + fq * 4;
;               #pragma unroll
;               for (int bj = 0; bj < 2; ++bj)
;                 #pragma unroll
;                 for (int n = 0; n < 2; ++n) {
;                   f32x4 v = acc[ai][bj][m][n] + xv[mm][bj][n];
;                   ss += (v[0] * v[0] + v[1] * v[1]) + (v[2] * v[2] + v[3] * v[3]);
;                   *reinterpret_cast<u32x2*>(hd + bj * 128 + n * 16) = pack4(v);
;                 }
;               ss += __shfl_xor(ss, 16); ss += __shfl_xor(ss, 32);
;               if (fq == 0) red[wc * 256 + lrow] = ss;
	v_pk_add_f32 v[90:91], v[90:91], v[132:133]
	v_pk_add_f32 v[88:89], v[88:89], v[130:131]
	v_fmac_f32_e32 v115, v94, v94
	v_add_f32_e32 v92, v92, v93
	v_cvt_pk_bf16_f32 v84, v84, v85
	v_mul_f32_e32 v85, v89, v89
	v_mul_f32_e32 v93, v91, v91
	v_add_f32_e32 v113, v113, v115
	v_fmac_f32_e32 v85, v88, v88
	v_fmac_f32_e32 v93, v90, v90
	v_add_f32_e32 v92, v113, v92
	v_add_f32_e32 v85, v85, v93
	v_add_f32_e32 v85, v92, v85
	s_waitcnt vmcnt(4)
	v_pk_add_f32 v[82:83], v[82:83], v[136:137]
	v_pk_add_f32 v[92:93], v[80:81], v[134:135]
	v_mul_f32_e32 v81, v83, v83
	v_mul_f32_e32 v80, v93, v93
	v_fmac_f32_e32 v80, v92, v92
	v_fmac_f32_e32 v81, v82, v82
	v_add_f32_e32 v80, v80, v81
	v_add_f32_e32 v80, v85, v80
	v_mov_b32_e32 v81, v80
	s_nop 1
	v_permlane16_swap_b32_e32 v80, v81
	v_cvt_pk_bf16_f32 v85, v86, v87
	v_mov_b32_e32 v198, v84
	v_mov_b32_e32 v199, v85
	v_bfe_u32 v194, v252, 4, 1
	v_mul_u32_u24_e32 v194, 24, v194
	v_mov_b32_e32 v195, 0
	v_lshl_add_u64 v[200:201], v[138:139], 0, v[194:195]
	v_permlane16_swap_b32_e32 v196, v198
	v_permlane16_swap_b32_e32 v197, v199
	global_store_dwordx4 v[200:201], v[196:199], off
	s_nop 1
	v_cvt_pk_bf16_f32 v84, v88, v89
	v_cvt_pk_bf16_f32 v85, v90, v91
	s_waitcnt lgkmcnt(0)
	v_add_f32_e32 v80, v80, v81
	v_mov_b32_e32 v81, v80
	s_nop 1
	v_permlane32_swap_b32_e32 v80, v81
	v_mov_b32_e32 v196, v84
	v_mov_b32_e32 v197, v85
	v_cvt_pk_bf16_f32 v84, v92, v93
	v_cvt_pk_bf16_f32 v85, v82, v83
	v_mov_b32_e32 v198, v84
	v_mov_b32_e32 v199, v85
	v_bfe_u32 v194, v252, 4, 1
	v_mul_u32_u24_e32 v194, 24, v194
	v_mov_b32_e32 v195, 0
	v_lshl_add_u64 v[200:201], v[138:139], 0, v[194:195]
	v_permlane16_swap_b32_e32 v196, v198
	v_permlane16_swap_b32_e32 v197, v199
	global_store_dwordx4 v[200:201], v[196:199], off offset:256
	s_nop 1
	s_and_saveexec_b64 s[0:1], vcc
	s_cbranch_execz .LBB0_611
	s_waitcnt lgkmcnt(0)
	v_add_f32_e32 v80, v80, v81
	ds_write_b32 v118, v80 offset:128
.LBB0_611:
	s_or_b64 exec, exec, s[0:1]
	v_add3_u32 v80, s40, v151, 48
	s_waitcnt lgkmcnt(0)
	v_ashrrev_i32_e32 v81, 31, v80
	v_lshlrev_b64 v[80:81], 11, v[80:81]
	v_lshl_add_u64 v[80:81], s[26:27], 0, v[80:81]
	v_lshl_add_u64 v[80:81], s[42:43], 1, v[80:81]
	s_waitcnt vmcnt(5)
	v_pk_add_f32 v[76:77], v[76:77], v[108:109]
	v_lshl_add_u64 v[80:81], v[80:81], 0, v[146:147]
	v_mov_b32_e32 v113, v147
	v_mul_f32_e32 v82, v77, v77
	v_lshl_add_u64 v[80:81], v[80:81], 0, v[112:113]
	v_pk_add_f32 v[78:79], v[78:79], v[110:111]
	v_fmac_f32_e32 v82, v76, v76
	v_cvt_pk_bf16_f32 v76, v76, v77
	v_cvt_pk_bf16_f32 v77, v78, v79
	s_waitcnt vmcnt(4)
	v_pk_add_f32 v[70:71], v[70:71], v[106:107]
	v_pk_add_f32 v[68:69], v[68:69], v[104:105]
	v_mov_b32_e32 v196, v76
	v_mov_b32_e32 v197, v77
	v_mul_f32_e32 v76, v69, v69
	v_mul_f32_e32 v77, v71, v71
	v_mul_f32_e32 v83, v79, v79
	v_fmac_f32_e32 v76, v68, v68
	v_fmac_f32_e32 v77, v70, v70
	s_waitcnt vmcnt(3)
	v_pk_add_f32 v[74:75], v[74:75], v[102:103]
	v_pk_add_f32 v[72:73], v[72:73], v[100:101]
	v_fmac_f32_e32 v83, v78, v78
	v_add_f32_e32 v76, v76, v77
	v_cvt_pk_bf16_f32 v68, v68, v69
	v_mul_f32_e32 v69, v73, v73
	v_mul_f32_e32 v77, v75, v75
	v_add_f32_e32 v82, v82, v83
	v_fmac_f32_e32 v69, v72, v72
	v_fmac_f32_e32 v77, v74, v74
	v_add_f32_e32 v76, v82, v76
	v_add_f32_e32 v69, v69, v77
	v_add_f32_e32 v69, v76, v69
	s_waitcnt vmcnt(2)
	v_pk_add_f32 v[66:67], v[66:67], v[98:99]
	v_pk_add_f32 v[76:77], v[64:65], v[96:97]
	v_mul_f32_e32 v65, v67, v67
	v_mul_f32_e32 v64, v77, v77
	v_fmac_f32_e32 v64, v76, v76
	v_fmac_f32_e32 v65, v66, v66
	v_add_f32_e32 v64, v64, v65
	v_add_f32_e32 v64, v69, v64
	v_mov_b32_e32 v65, v64
	s_nop 1
	v_permlane16_swap_b32_e32 v64, v65
	v_cvt_pk_bf16_f32 v69, v70, v71
	v_mov_b32_e32 v198, v68
	v_mov_b32_e32 v199, v69
	v_bfe_u32 v194, v252, 4, 1
	v_mul_u32_u24_e32 v194, 24, v194
	v_mov_b32_e32 v195, 0
	v_lshl_add_u64 v[200:201], v[80:81], 0, v[194:195]
	v_permlane16_swap_b32_e32 v196, v198
	v_permlane16_swap_b32_e32 v197, v199
	global_store_dwordx4 v[200:201], v[196:199], off
	s_nop 1
	v_cvt_pk_bf16_f32 v68, v72, v73
	v_cvt_pk_bf16_f32 v69, v74, v75
	s_waitcnt lgkmcnt(0)
	v_add_f32_e32 v64, v64, v65
	v_mov_b32_e32 v65, v64
	s_nop 1
	v_permlane32_swap_b32_e32 v64, v65
	v_mov_b32_e32 v196, v68
	v_mov_b32_e32 v197, v69
	v_cvt_pk_bf16_f32 v68, v76, v77
	v_cvt_pk_bf16_f32 v69, v66, v67
	v_mov_b32_e32 v198, v68
	v_mov_b32_e32 v199, v69
	v_bfe_u32 v194, v252, 4, 1
	v_mul_u32_u24_e32 v194, 24, v194
	v_mov_b32_e32 v195, 0
	v_lshl_add_u64 v[200:201], v[80:81], 0, v[194:195]
	v_permlane16_swap_b32_e32 v196, v198
	v_permlane16_swap_b32_e32 v197, v199
	global_store_dwordx4 v[200:201], v[196:199], off offset:256
	s_nop 1
	s_and_saveexec_b64 s[0:1], vcc
	s_cbranch_execz .LBB0_613
	s_waitcnt lgkmcnt(0)
	v_add_f32_e32 v64, v64, v65
	ds_write_b32 v118, v64 offset:192
; __device__ __forceinline__ u32x2 pack4(float a, float b, float c, float d) { return u32x2{cvtpk(a, b), cvtpk(c, d)}; }
; __device__ __forceinline__ u32x2 pack4(const f32x4& v) { return u32x2{cvtpk(v[0], v[1]), cvtpk(v[2], v[3])}; }
; #define SBAR() __builtin_amdgcn_sched_barrier(0)
; __global__ void __launch_bounds__(512) fwd_megakernel(Params p) {
;     ...
;         for (int ai = 0; ai < 2; ++ai)
;           #pragma unroll
;           for (int mp = 0; mp < 2; ++mp) { SBAR();
;             f32x4 xv[2][2][2];
;             #pragma unroll
;             for (int mm = 0; mm < 2; ++mm) {
;               const float* xr = xrow_ptr(p, brow + ai * 128 + wr * 64 + (mp * 2 + mm) * 16 + fr) + pn * 256 + wc * 32 + fq * 4;
;               #pragma unroll
;               for (int bj = 0; bj < 2; ++bj)
;                 #pragma unroll
;                 for (int n = 0; n < 2; ++n) xv[mm][bj][n] = *reinterpret_cast<const f32x4*>(xr + bj * 128 + n * 16);
;             }
;             SBAR();
;             #pragma unroll
;             for (int mm = 0; mm < 2; ++mm) {
;               const int m = mp * 2 + mm;
;               int lrow = ai * 128 + wr * 64 + m * 16 + fr, row = brow + lrow; float ss = 0.f;
;               bf16* hd = p_h1b + (long)row * DM + pn * 256 + wc * 32 + fq * 4;
;               #pragma unroll
;               for (int bj = 0; bj < 2; ++bj)
;                 #pragma unroll
;                 for (int n = 0; n < 2; ++n) {
;                   f32x4 v = acc[ai][bj][m][n] + xv[mm][bj][n];
;                   ss += (v[0] * v[0] + v[1] * v[1]) + (v[2] * v[2] + v[3] * v[3]);
;                   *reinterpret_cast<u32x2*>(hd + bj * 128 + n * 16) = pack4(v);
;                 }
;               ss += __shfl_xor(ss, 16); ss += __shfl_xor(ss, 32);
;               if (fq == 0) red[wc * 256 + lrow] = ss;
.LBB0_613:
	s_or_b64 exec, exec, s[0:1]
	v_add_u32_e32 v98, 0x80, v148
	v_add_u32_e32 v64, 0xffff8080, v148
	v_ashrrev_i32_e32 v99, 31, v98
	v_cmp_gt_i32_e64 s[0:1], s60, v98
	v_mov_b32_e32 v68, s39
	v_mov_b32_e32 v69, s37
	s_waitcnt lgkmcnt(0)
	v_cndmask_b32_e64 v65, 0, v99, s[0:1]
	v_cndmask_b32_e64 v64, v64, v98, s[0:1]
	v_mov_b32_e32 v70, s38
	v_mov_b32_e32 v71, s36
	v_cndmask_b32_e64 v67, v68, v69, s[0:1]
	v_cndmask_b32_e64 v66, v70, v71, s[0:1]
	v_lshlrev_b64 v[64:65], 12, v[64:65]
	v_lshl_add_u64 v[64:65], v[66:67], 0, v[64:65]
	v_lshl_add_u64 v[64:65], v[64:65], 0, s[44:45]
	v_mov_b32_e32 v115, v147
	v_lshl_add_u64 v[64:65], v[64:65], 0, v[114:115]
	v_mov_b32_e32 v117, v147
	v_lshl_add_u64 v[64:65], v[64:65], 0, v[116:117]
	v_add_u32_e32 v80, 0x90, v148
	global_load_dwordx4 v[82:85], v[64:65], off
	global_load_dwordx4 v[86:89], v[64:65], off offset:64
	global_load_dwordx4 v[90:93], v[64:65], off offset:512
	global_load_dwordx4 v[94:97], v[64:65], off offset:576
	v_add_u32_e32 v64, 0xffff8090, v148
	v_ashrrev_i32_e32 v81, 31, v80
	v_cmp_gt_i32_e64 s[0:1], s60, v80
	s_nop 1
	v_cndmask_b32_e64 v65, 0, v81, s[0:1]
	v_cndmask_b32_e64 v64, v64, v80, s[0:1]
	v_cndmask_b32_e64 v67, v68, v69, s[0:1]
	v_cndmask_b32_e64 v66, v70, v71, s[0:1]
	v_lshlrev_b64 v[64:65], 12, v[64:65]
	v_lshl_add_u64 v[64:65], v[66:67], 0, v[64:65]
	v_lshl_add_u64 v[64:65], v[64:65], 0, s[44:45]
	v_lshl_add_u64 v[64:65], v[64:65], 0, v[114:115]
	v_lshl_add_u64 v[64:65], v[64:65], 0, v[116:117]
	global_load_dwordx4 v[76:79], v[64:65], off
	global_load_dwordx4 v[72:75], v[64:65], off offset:64
	global_load_dwordx4 v[68:71], v[64:65], off offset:512
	s_nop 0
	global_load_dwordx4 v[64:67], v[64:65], off offset:576
	v_lshlrev_b64 v[98:99], 11, v[98:99]
	v_lshl_add_u64 v[98:99], s[26:27], 0, v[98:99]
	v_lshl_add_u64 v[98:99], s[42:43], 1, v[98:99]
	s_waitcnt vmcnt(7)
	v_pk_add_f32 v[60:61], v[60:61], v[82:83]
	v_lshl_add_u64 v[98:99], v[98:99], 0, v[146:147]
	v_mul_f32_e32 v82, v61, v61
	v_lshl_add_u64 v[98:99], v[98:99], 0, v[112:113]
	v_pk_add_f32 v[62:63], v[62:63], v[84:85]
	v_fmac_f32_e32 v82, v60, v60
	v_cvt_pk_bf16_f32 v60, v60, v61
	v_cvt_pk_bf16_f32 v61, v62, v63
	s_waitcnt vmcnt(6)
	v_pk_add_f32 v[58:59], v[58:59], v[88:89]
	v_pk_add_f32 v[56:57], v[56:57], v[86:87]
	v_mov_b32_e32 v196, v60
	v_mov_b32_e32 v197, v61
	v_mul_f32_e32 v60, v57, v57
	v_mul_f32_e32 v61, v59, v59
	v_mul_f32_e32 v83, v63, v63
	v_fmac_f32_e32 v60, v56, v56
	v_fmac_f32_e32 v61, v58, v58
	s_waitcnt vmcnt(5)
	v_pk_add_f32 v[54:55], v[54:55], v[92:93]
	v_pk_add_f32 v[52:53], v[52:53], v[90:91]
	v_fmac_f32_e32 v83, v62, v62
	v_add_f32_e32 v60, v60, v61
	v_cvt_pk_bf16_f32 v56, v56, v57
	v_mul_f32_e32 v57, v53, v53
	v_mul_f32_e32 v61, v55, v55
	v_add_f32_e32 v82, v82, v83
	v_fmac_f32_e32 v57, v52, v52
	v_fmac_f32_e32 v61, v54, v54
	v_add_f32_e32 v60, v82, v60
	v_add_f32_e32 v57, v57, v61
	v_add_f32_e32 v57, v60, v57
	s_waitcnt vmcnt(4)
	v_pk_add_f32 v[50:51], v[50:51], v[96:97]
	v_pk_add_f32 v[60:61], v[48:49], v[94:95]
	v_mul_f32_e32 v49, v51, v51
	v_mul_f32_e32 v48, v61, v61
	v_fmac_f32_e32 v48, v60, v60
	v_fmac_f32_e32 v49, v50, v50
	v_add_f32_e32 v48, v48, v49
	v_add_f32_e32 v48, v57, v48
	v_mov_b32_e32 v49, v48
	s_nop 1
	v_permlane16_swap_b32_e32 v48, v49
	v_cvt_pk_bf16_f32 v57, v58, v59
	v_mov_b32_e32 v198, v56
	v_mov_b32_e32 v199, v57
	v_bfe_u32 v194, v252, 4, 1
	v_mul_u32_u24_e32 v194, 24, v194
	v_mov_b32_e32 v195, 0
	v_lshl_add_u64 v[200:201], v[98:99], 0, v[194:195]
	v_permlane16_swap_b32_e32 v196, v198
	v_permlane16_swap_b32_e32 v197, v199
	global_store_dwordx4 v[200:201], v[196:199], off
	s_nop 1
	v_cvt_pk_bf16_f32 v52, v52, v53
	v_cvt_pk_bf16_f32 v53, v54, v55
	s_waitcnt lgkmcnt(0)
	v_add_f32_e32 v48, v48, v49
	v_mov_b32_e32 v49, v48
	s_nop 1
	v_permlane32_swap_b32_e32 v48, v49
	v_mov_b32_e32 v196, v52
	v_mov_b32_e32 v197, v53
	v_cvt_pk_bf16_f32 v52, v60, v61
	v_cvt_pk_bf16_f32 v53, v50, v51
	v_mov_b32_e32 v198, v52
	v_mov_b32_e32 v199, v53
	v_bfe_u32 v194, v252, 4, 1
	v_mul_u32_u24_e32 v194, 24, v194
	v_mov_b32_e32 v195, 0
	v_lshl_add_u64 v[200:201], v[98:99], 0, v[194:195]
	v_permlane16_swap_b32_e32 v196, v198
	v_permlane16_swap_b32_e32 v197, v199
	global_store_dwordx4 v[200:201], v[196:199], off offset:256
	s_nop 1
	s_and_saveexec_b64 s[0:1], vcc
	s_cbranch_execz .LBB0_615
	s_waitcnt lgkmcnt(0)
	v_add_f32_e32 v48, v48, v49
	ds_write_b32 v118, v48 offset:512
; __device__ __forceinline__ u32x2 pack4(float a, float b, float c, float d) { return u32x2{cvtpk(a, b), cvtpk(c, d)}; }
; __device__ __forceinline__ u32x2 pack4(const f32x4& v) { return u32x2{cvtpk(v[0], v[1]), cvtpk(v[2], v[3])}; }
; #define SBAR() __builtin_amdgcn_sched_barrier(0)
; __global__ void __launch_bounds__(512) fwd_megakernel(Params p) {
;     ...
;         for (int ai = 0; ai < 2; ++ai)
;           #pragma unroll
;           for (int mp = 0; mp < 2; ++mp) { SBAR();
;             f32x4 xv[2][2][2];
;             #pragma unroll
;             for (int mm = 0; mm < 2; ++mm) {
;               const float* xr = xrow_ptr(p, brow + ai * 128 + wr * 64 + (mp * 2 + mm) * 16 + fr) + pn * 256 + wc * 32 + fq * 4;
;               #pragma unroll
;               for (int bj = 0; bj < 2; ++bj)
;                 #pragma unroll
;                 for (int n = 0; n < 2; ++n) xv[mm][bj][n] = *reinterpret_cast<const f32x4*>(xr + bj * 128 + n * 16);
;             }
;             SBAR();
;             #pragma unroll
;             for (int mm = 0; mm < 2; ++mm) {
;               const int m = mp * 2 + mm;
;               int lrow = ai * 128 + wr * 64 + m * 16 + fr, row = brow + lrow; float ss = 0.f;
;               bf16* hd = p_h1b + (long)row * DM + pn * 256 + wc * 32 + fq * 4;
;               #pragma unroll
;               for (int bj = 0; bj < 2; ++bj)
;                 #pragma unroll
;                 for (int n = 0; n < 2; ++n) {
;                   f32x4 v = acc[ai][bj][m][n] + xv[mm][bj][n];
;                   ss += (v[0] * v[0] + v[1] * v[1]) + (v[2] * v[2] + v[3] * v[3]);
;                   *reinterpret_cast<u32x2*>(hd + bj * 128 + n * 16) = pack4(v);
;                 }
;               ss += __shfl_xor(ss, 16); ss += __shfl_xor(ss, 32);
;               if (fq == 0) red[wc * 256 + lrow] = ss;
.LBB0_615:
	s_or_b64 exec, exec, s[0:1]
	s_waitcnt lgkmcnt(0)
	v_lshlrev_b64 v[48:49], 11, v[80:81]
	v_lshl_add_u64 v[48:49], s[26:27], 0, v[48:49]
	v_lshl_add_u64 v[48:49], s[42:43], 1, v[48:49]
	s_waitcnt vmcnt(5)
	v_pk_add_f32 v[44:45], v[44:45], v[76:77]
	v_lshl_add_u64 v[48:49], v[48:49], 0, v[146:147]
	v_mov_b32_e32 v113, v147
	v_mul_f32_e32 v50, v45, v45
	v_lshl_add_u64 v[48:49], v[48:49], 0, v[112:113]
	v_pk_add_f32 v[46:47], v[46:47], v[78:79]
	v_fmac_f32_e32 v50, v44, v44
	v_cvt_pk_bf16_f32 v44, v44, v45
	v_cvt_pk_bf16_f32 v45, v46, v47
	s_waitcnt vmcnt(4)
	v_pk_add_f32 v[42:43], v[42:43], v[74:75]
	v_pk_add_f32 v[40:41], v[40:41], v[72:73]
	v_mov_b32_e32 v196, v44
	v_mov_b32_e32 v197, v45
	v_mul_f32_e32 v44, v41, v41
	v_mul_f32_e32 v45, v43, v43
	v_mul_f32_e32 v51, v47, v47
	v_fmac_f32_e32 v44, v40, v40
	v_fmac_f32_e32 v45, v42, v42
	s_waitcnt vmcnt(3)
	v_pk_add_f32 v[38:39], v[38:39], v[70:71]
	v_pk_add_f32 v[36:37], v[36:37], v[68:69]
	v_fmac_f32_e32 v51, v46, v46
	v_add_f32_e32 v44, v44, v45
	v_cvt_pk_bf16_f32 v40, v40, v41
	v_mul_f32_e32 v41, v37, v37
	v_mul_f32_e32 v45, v39, v39
	v_add_f32_e32 v50, v50, v51
	v_fmac_f32_e32 v41, v36, v36
	v_fmac_f32_e32 v45, v38, v38
	v_add_f32_e32 v44, v50, v44
	v_add_f32_e32 v41, v41, v45
	v_add_f32_e32 v41, v44, v41
	s_waitcnt vmcnt(2)
	v_pk_add_f32 v[34:35], v[34:35], v[66:67]
	v_pk_add_f32 v[44:45], v[32:33], v[64:65]
	v_mul_f32_e32 v33, v35, v35
	v_mul_f32_e32 v32, v45, v45
	v_fmac_f32_e32 v32, v44, v44
	v_fmac_f32_e32 v33, v34, v34
	v_add_f32_e32 v32, v32, v33
	v_add_f32_e32 v32, v41, v32
	v_mov_b32_e32 v33, v32
	s_nop 1
	v_permlane16_swap_b32_e32 v32, v33
	v_cvt_pk_bf16_f32 v41, v42, v43
	v_mov_b32_e32 v198, v40
	v_mov_b32_e32 v199, v41
	v_bfe_u32 v194, v252, 4, 1
	v_mul_u32_u24_e32 v194, 24, v194
	v_mov_b32_e32 v195, 0
	v_lshl_add_u64 v[200:201], v[48:49], 0, v[194:195]
	v_permlane16_swap_b32_e32 v196, v198
	v_permlane16_swap_b32_e32 v197, v199
	global_store_dwordx4 v[200:201], v[196:199], off
	s_nop 1
	v_cvt_pk_bf16_f32 v36, v36, v37
	v_cvt_pk_bf16_f32 v37, v38, v39
	s_waitcnt lgkmcnt(0)
	v_add_f32_e32 v32, v32, v33
	v_mov_b32_e32 v33, v32
	s_nop 1
	v_permlane32_swap_b32_e32 v32, v33
	v_mov_b32_e32 v196, v36
	v_mov_b32_e32 v197, v37
	v_cvt_pk_bf16_f32 v36, v44, v45
	v_cvt_pk_bf16_f32 v37, v34, v35
	v_mov_b32_e32 v198, v36
	v_mov_b32_e32 v199, v37
	v_bfe_u32 v194, v252, 4, 1
	v_mul_u32_u24_e32 v194, 24, v194
	v_mov_b32_e32 v195, 0
	v_lshl_add_u64 v[200:201], v[48:49], 0, v[194:195]
	v_permlane16_swap_b32_e32 v196, v198
	v_permlane16_swap_b32_e32 v197, v199
	global_store_dwordx4 v[200:201], v[196:199], off offset:256
	s_nop 1
	s_and_saveexec_b64 s[0:1], vcc
	s_cbranch_execz .LBB0_617
	s_waitcnt lgkmcnt(0)
	v_add_f32_e32 v32, v32, v33
	ds_write_b32 v118, v32 offset:576
.LBB0_617:
	s_or_b64 exec, exec, s[0:1]
	v_add_u32_e32 v66, 0xa0, v148
	v_add_u32_e32 v32, 0xffff80a0, v148
	v_ashrrev_i32_e32 v67, 31, v66
	v_cmp_gt_i32_e64 s[0:1], s60, v66
	v_mov_b32_e32 v36, s39
	v_mov_b32_e32 v37, s37
	s_waitcnt lgkmcnt(0)
	v_cndmask_b32_e64 v33, 0, v67, s[0:1]
	v_cndmask_b32_e64 v32, v32, v66, s[0:1]
	v_mov_b32_e32 v38, s38
	v_mov_b32_e32 v39, s36
	v_cndmask_b32_e64 v35, v36, v37, s[0:1]
	v_cndmask_b32_e64 v34, v38, v39, s[0:1]
	v_lshlrev_b64 v[32:33], 12, v[32:33]
	v_lshl_add_u64 v[32:33], v[34:35], 0, v[32:33]
	v_lshl_add_u64 v[32:33], v[32:33], 0, s[44:45]
	v_mov_b32_e32 v115, v147
	v_lshl_add_u64 v[32:33], v[32:33], 0, v[114:115]
	v_mov_b32_e32 v117, v147
	v_lshl_add_u64 v[32:33], v[32:33], 0, v[116:117]
	v_add_u32_e32 v48, 0xb0, v148
	global_load_dwordx4 v[50:53], v[32:33], off
	global_load_dwordx4 v[54:57], v[32:33], off offset:64
	global_load_dwordx4 v[58:61], v[32:33], off offset:512
	global_load_dwordx4 v[62:65], v[32:33], off offset:576
	v_add_u32_e32 v32, 0xffff80b0, v148
	v_ashrrev_i32_e32 v49, 31, v48
	v_cmp_gt_i32_e64 s[0:1], s60, v48
	s_nop 1
	v_cndmask_b32_e64 v33, 0, v49, s[0:1]
	v_cndmask_b32_e64 v32, v32, v48, s[0:1]
	v_cndmask_b32_e64 v35, v36, v37, s[0:1]
	v_cndmask_b32_e64 v34, v38, v39, s[0:1]
	v_lshlrev_b64 v[32:33], 12, v[32:33]
	v_lshl_add_u64 v[32:33], v[34:35], 0, v[32:33]
	v_lshl_add_u64 v[32:33], v[32:33], 0, s[44:45]
	v_lshl_add_u64 v[32:33], v[32:33], 0, v[114:115]
	v_lshl_add_u64 v[32:33], v[32:33], 0, v[116:117]
	global_load_dwordx4 v[44:47], v[32:33], off
	global_load_dwordx4 v[40:43], v[32:33], off offset:64
	global_load_dwordx4 v[36:39], v[32:33], off offset:512
	s_nop 0
	global_load_dwordx4 v[32:35], v[32:33], off offset:576
	v_lshlrev_b64 v[66:67], 11, v[66:67]
	v_lshl_add_u64 v[66:67], s[26:27], 0, v[66:67]
	v_lshl_add_u64 v[66:67], s[42:43], 1, v[66:67]
	s_waitcnt vmcnt(7)
	v_pk_add_f32 v[28:29], v[28:29], v[50:51]
	v_lshl_add_u64 v[66:67], v[66:67], 0, v[146:147]
	v_mul_f32_e32 v50, v29, v29
	v_lshl_add_u64 v[66:67], v[66:67], 0, v[112:113]
	v_pk_add_f32 v[30:31], v[30:31], v[52:53]
	v_fmac_f32_e32 v50, v28, v28
	v_cvt_pk_bf16_f32 v28, v28, v29
	v_cvt_pk_bf16_f32 v29, v30, v31
	s_waitcnt vmcnt(6)
; __device__ __forceinline__ u32x2 pack4(float a, float b, float c, float d) { return u32x2{cvtpk(a, b), cvtpk(c, d)}; }
; __device__ __forceinline__ u32x2 pack4(const f32x4& v) { return u32x2{cvtpk(v[0], v[1]), cvtpk(v[2], v[3])}; }
; #define SBAR() __builtin_amdgcn_sched_barrier(0)
; __global__ void __launch_bounds__(512) fwd_megakernel(Params p) {
;     ...
;         for (int ai = 0; ai < 2; ++ai)
;           #pragma unroll
;           for (int mp = 0; mp < 2; ++mp) { SBAR();
;             f32x4 xv[2][2][2];
;             #pragma unroll
;             for (int mm = 0; mm < 2; ++mm) {
;               const float* xr = xrow_ptr(p, brow + ai * 128 + wr * 64 + (mp * 2 + mm) * 16 + fr) + pn * 256 + wc * 32 + fq * 4;
;               #pragma unroll
;               for (int bj = 0; bj < 2; ++bj)
;                 #pragma unroll
;                 for (int n = 0; n < 2; ++n) xv[mm][bj][n] = *reinterpret_cast<const f32x4*>(xr + bj * 128 + n * 16);
;             }
;             SBAR();
;             #pragma unroll
;             for (int mm = 0; mm < 2; ++mm) {
;               const int m = mp * 2 + mm;
;               int lrow = ai * 128 + wr * 64 + m * 16 + fr, row = brow + lrow; float ss = 0.f;
;               bf16* hd = p_h1b + (long)row * DM + pn * 256 + wc * 32 + fq * 4;
;               #pragma unroll
;               for (int bj = 0; bj < 2; ++bj)
;                 #pragma unroll
;                 for (int n = 0; n < 2; ++n) {
;                   f32x4 v = acc[ai][bj][m][n] + xv[mm][bj][n];
;                   ss += (v[0] * v[0] + v[1] * v[1]) + (v[2] * v[2] + v[3] * v[3]);
;                   *reinterpret_cast<u32x2*>(hd + bj * 128 + n * 16) = pack4(v);
;                 }
;               ss += __shfl_xor(ss, 16); ss += __shfl_xor(ss, 32);
;               if (fq == 0) red[wc * 256 + lrow] = ss;
	v_pk_add_f32 v[26:27], v[26:27], v[56:57]
	v_pk_add_f32 v[24:25], v[24:25], v[54:55]
	v_mov_b32_e32 v196, v28
	v_mov_b32_e32 v197, v29
	v_mul_f32_e32 v28, v25, v25
	v_mul_f32_e32 v29, v27, v27
	v_mul_f32_e32 v51, v31, v31
	v_fmac_f32_e32 v28, v24, v24
	v_fmac_f32_e32 v29, v26, v26
	s_waitcnt vmcnt(5)
	v_pk_add_f32 v[22:23], v[22:23], v[60:61]
	v_pk_add_f32 v[20:21], v[20:21], v[58:59]
	v_fmac_f32_e32 v51, v30, v30
	v_add_f32_e32 v28, v28, v29
	v_cvt_pk_bf16_f32 v24, v24, v25
	v_mul_f32_e32 v25, v21, v21
	v_mul_f32_e32 v29, v23, v23
	v_add_f32_e32 v50, v50, v51
	v_fmac_f32_e32 v25, v20, v20
	v_fmac_f32_e32 v29, v22, v22
	v_add_f32_e32 v28, v50, v28
	v_add_f32_e32 v25, v25, v29
	v_add_f32_e32 v25, v28, v25
	s_waitcnt vmcnt(4)
	v_pk_add_f32 v[18:19], v[18:19], v[64:65]
	v_pk_add_f32 v[28:29], v[16:17], v[62:63]
	v_mul_f32_e32 v17, v19, v19
	v_mul_f32_e32 v16, v29, v29
	v_fmac_f32_e32 v16, v28, v28
	v_fmac_f32_e32 v17, v18, v18
	v_add_f32_e32 v16, v16, v17
	v_add_f32_e32 v16, v25, v16
	v_mov_b32_e32 v17, v16
	s_nop 1
	v_permlane16_swap_b32_e32 v16, v17
	v_cvt_pk_bf16_f32 v25, v26, v27
	v_mov_b32_e32 v198, v24
	v_mov_b32_e32 v199, v25
	v_bfe_u32 v194, v252, 4, 1
	v_mul_u32_u24_e32 v194, 24, v194
	v_mov_b32_e32 v195, 0
	v_lshl_add_u64 v[200:201], v[66:67], 0, v[194:195]
	v_permlane16_swap_b32_e32 v196, v198
	v_permlane16_swap_b32_e32 v197, v199
	global_store_dwordx4 v[200:201], v[196:199], off
	s_nop 1
	v_cvt_pk_bf16_f32 v20, v20, v21
	v_cvt_pk_bf16_f32 v21, v22, v23
	s_waitcnt lgkmcnt(0)
	v_add_f32_e32 v16, v16, v17
	v_mov_b32_e32 v17, v16
	s_nop 1
	v_permlane32_swap_b32_e32 v16, v17
	v_mov_b32_e32 v196, v20
	v_mov_b32_e32 v197, v21
	v_cvt_pk_bf16_f32 v20, v28, v29
	v_cvt_pk_bf16_f32 v21, v18, v19
	v_mov_b32_e32 v198, v20
	v_mov_b32_e32 v199, v21
	v_bfe_u32 v194, v252, 4, 1
	v_mul_u32_u24_e32 v194, 24, v194
	v_mov_b32_e32 v195, 0
	v_lshl_add_u64 v[200:201], v[66:67], 0, v[194:195]
	v_permlane16_swap_b32_e32 v196, v198
	v_permlane16_swap_b32_e32 v197, v199
	global_store_dwordx4 v[200:201], v[196:199], off offset:256
	s_nop 1
	s_and_saveexec_b64 s[0:1], vcc
	s_cbranch_execz .LBB0_619
	s_waitcnt lgkmcnt(0)
	v_add_f32_e32 v16, v16, v17
	ds_write_b32 v118, v16 offset:640
.LBB0_619:
	s_or_b64 exec, exec, s[0:1]
	s_waitcnt lgkmcnt(0)
	v_lshlrev_b64 v[16:17], 11, v[48:49]
	v_lshl_add_u64 v[16:17], s[26:27], 0, v[16:17]
	v_lshl_add_u64 v[16:17], s[42:43], 1, v[16:17]
	s_waitcnt vmcnt(5)
	v_pk_add_f32 v[12:13], v[12:13], v[44:45]
	v_lshl_add_u64 v[16:17], v[16:17], 0, v[146:147]
	v_mov_b32_e32 v113, v147
	v_mul_f32_e32 v18, v13, v13
	v_lshl_add_u64 v[16:17], v[16:17], 0, v[112:113]
	v_pk_add_f32 v[14:15], v[14:15], v[46:47]
	v_fmac_f32_e32 v18, v12, v12
	v_cvt_pk_bf16_f32 v12, v12, v13
	v_cvt_pk_bf16_f32 v13, v14, v15
	s_waitcnt vmcnt(4)
	v_pk_add_f32 v[10:11], v[10:11], v[42:43]
	v_pk_add_f32 v[8:9], v[8:9], v[40:41]
	v_mov_b32_e32 v196, v12
	v_mov_b32_e32 v197, v13
	v_mul_f32_e32 v12, v9, v9
	v_mul_f32_e32 v13, v11, v11
	v_mul_f32_e32 v19, v15, v15
	v_fmac_f32_e32 v12, v8, v8
	v_fmac_f32_e32 v13, v10, v10
	s_waitcnt vmcnt(3)
	v_pk_add_f32 v[6:7], v[6:7], v[38:39]
	v_pk_add_f32 v[4:5], v[4:5], v[36:37]
	v_fmac_f32_e32 v19, v14, v14
	v_add_f32_e32 v12, v12, v13
	v_cvt_pk_bf16_f32 v8, v8, v9
	v_mul_f32_e32 v9, v5, v5
	v_mul_f32_e32 v13, v7, v7
	v_add_f32_e32 v18, v18, v19
	v_fmac_f32_e32 v9, v4, v4
	v_fmac_f32_e32 v13, v6, v6
	v_add_f32_e32 v12, v18, v12
	v_add_f32_e32 v9, v9, v13
	v_add_f32_e32 v9, v12, v9
	s_waitcnt vmcnt(2)
	v_pk_add_f32 v[2:3], v[2:3], v[34:35]
	v_pk_add_f32 v[12:13], v[0:1], v[32:33]
	v_mul_f32_e32 v1, v3, v3
	v_mul_f32_e32 v0, v13, v13
	v_fmac_f32_e32 v0, v12, v12
	v_fmac_f32_e32 v1, v2, v2
	v_add_f32_e32 v0, v0, v1
	v_add_f32_e32 v0, v9, v0
	v_mov_b32_e32 v1, v0
	s_nop 1
	v_permlane16_swap_b32_e32 v0, v1
	v_cvt_pk_bf16_f32 v9, v10, v11
	v_mov_b32_e32 v198, v8
	v_mov_b32_e32 v199, v9
	v_bfe_u32 v194, v252, 4, 1
	v_mul_u32_u24_e32 v194, 24, v194
	v_mov_b32_e32 v195, 0
	v_lshl_add_u64 v[200:201], v[16:17], 0, v[194:195]
	v_permlane16_swap_b32_e32 v196, v198
	v_permlane16_swap_b32_e32 v197, v199
	global_store_dwordx4 v[200:201], v[196:199], off
	s_nop 1
	v_cvt_pk_bf16_f32 v4, v4, v5
	v_cvt_pk_bf16_f32 v5, v6, v7
	s_waitcnt lgkmcnt(0)
	v_add_f32_e32 v0, v0, v1
	v_mov_b32_e32 v1, v0
	s_nop 1
	v_permlane32_swap_b32_e32 v0, v1
	v_mov_b32_e32 v196, v4
	v_mov_b32_e32 v197, v5
	v_cvt_pk_bf16_f32 v4, v12, v13
	v_cvt_pk_bf16_f32 v5, v2, v3
	v_mov_b32_e32 v198, v4
	v_mov_b32_e32 v199, v5
	v_bfe_u32 v194, v252, 4, 1
	v_mul_u32_u24_e32 v194, 24, v194
	v_mov_b32_e32 v195, 0
	v_lshl_add_u64 v[200:201], v[16:17], 0, v[194:195]
	v_permlane16_swap_b32_e32 v196, v198
	v_permlane16_swap_b32_e32 v197, v199
	global_store_dwordx4 v[200:201], v[196:199], off offset:256
	s_nop 1
	s_and_saveexec_b64 s[0:1], vcc
	s_cbranch_execz .LBB0_621
	s_waitcnt lgkmcnt(0)
	v_add_f32_e32 v0, v0, v1
	ds_write_b32 v118, v0 offset:704

; __device__ __forceinline__ u32x2 pack4(float a, float b, float c, float d) { return u32x2{cvtpk(a, b), cvtpk(c, d)}; }
; __device__ __forceinline__ u32x2 pack4(const f32x4& v) { return u32x2{cvtpk(v[0], v[1]), cvtpk(v[2], v[3])}; }
; #define SBAR() __builtin_amdgcn_sched_barrier(0)
; __global__ void __launch_bounds__(512) fwd_megakernel(Params p) {
;     ...
;         for (int ai = 0; ai < 2; ++ai) { SBAR();
;           u32x2 hv[4][2][2];
;           #pragma unroll
;           for (int m = 0; m < 4; ++m) {
;             const bf16* hr = p_h1b + (long)(brow + ai * 128 + wr * 64 + m * 16 + fr) * DM + pn * 256 + wc * 32 + fq * 4;
;             #pragma unroll
;             for (int bj = 0; bj < 2; ++bj)
;               #pragma unroll
;               for (int n = 0; n < 2; ++n) hv[m][bj][n] = *reinterpret_cast<const u32x2*>(hr + bj * 128 + n * 16);
;           }
;           SBAR();
;           #pragma unroll
;           for (int m = 0; m < 4; ++m) {
;             int lrow = ai * 128 + wr * 64 + m * 16 + fr, row = brow + lrow; float ss = 0.f;
;             bf16* od = p_h2b + (long)row * DM + pn * 256 + wc * 32 + fq * 4;
;             #pragma unroll
;             for (int bj = 0; bj < 2; ++bj)
;               #pragma unroll
;               for (int n = 0; n < 2; ++n) {
;                 const u32x2 hw = hv[m][bj][n];
;                 f32x4 v = acc[ai][bj][m][n];
;                 v[0] += __uint_as_float(hw[0] << 16); v[1] += __uint_as_float(hw[0] & 0xffff0000u);
;                 v[2] += __uint_as_float(hw[1] << 16); v[3] += __uint_as_float(hw[1] & 0xffff0000u);
;                 ss += (v[0] * v[0] + v[1] * v[1]) + (v[2] * v[2] + v[3] * v[3]);
;                 *reinterpret_cast<u32x2*>(od + bj * 128 + n * 16) = pack4(v);
;               }
;             ss += __shfl_xor(ss, 16); ss += __shfl_xor(ss, 32);
;             if (fq == 0) red[wc * 256 + lrow] = ss;
;           }
.LBB0_749:
	v_mov_b32_e32 v128, v252
	s_waitcnt lgkmcnt(0)
	s_barrier
	s_nop 0
	v_bfe_u32 v162, v128, 6, 2
	v_and_b32_e32 v130, 15, v128
	v_bfe_u32 v163, v128, 4, 2
	v_ashrrev_i32_e32 v128, 2, v128
	v_and_or_b32 v161, v128, s51, v130
	v_cmp_eq_u32_e32 vcc, 0, v163
	v_lshl_add_u32 v176, v162, 10, s69
	s_ashr_i32 s31, s30, 31
	s_lshl_b64 s[0:1], s[30:31], 1
	s_add_u32 s36, s26, s0
	v_add_u32_e32 v130, s29, v161
	s_addc_u32 s37, s27, s1
	v_lshlrev_b32_e32 v128, 6, v162
	v_lshl_add_u64 v[132:133], s[36:37], 0, v[128:129]
	v_lshlrev_b32_e32 v164, 3, v163
	v_mov_b32_e32 v165, v129
	v_ashrrev_i32_e32 v131, 31, v130
	v_lshl_add_u64 v[132:133], v[132:133], 0, v[164:165]
	v_lshlrev_b64 v[166:167], 11, v[130:131]
	v_lshl_add_u64 v[134:135], v[132:133], 0, v[166:167]
	v_bfe_u32 v208, v252, 4, 1
	v_mul_u32_u24_e32 v208, 24, v208
	v_mov_b32_e32 v209, 0
	v_lshl_add_u64 v[198:199], v[134:135], 0, v[208:209]
	global_load_dwordx4 v[168:171], v[198:199], off
	global_load_dwordx4 v[172:175], v[198:199], off offset:256
	v_or_b32_e32 v134, 16, v130
	v_ashrrev_i32_e32 v135, 31, v134
	v_lshlrev_b64 v[134:135], 11, v[134:135]
	v_lshl_add_u64 v[134:135], v[132:133], 0, v[134:135]
	v_lshl_add_u64 v[198:199], v[134:135], 0, v[208:209]
	global_load_dwordx4 v[156:159], v[198:199], off
	global_load_dwordx4 v[152:155], v[198:199], off offset:256
	v_or_b32_e32 v134, 32, v130
	v_ashrrev_i32_e32 v135, 31, v134
	v_lshlrev_b64 v[134:135], 11, v[134:135]
	v_lshl_add_u64 v[134:135], v[132:133], 0, v[134:135]
	v_lshl_add_u64 v[198:199], v[134:135], 0, v[208:209]
	global_load_dwordx4 v[148:151], v[198:199], off
	global_load_dwordx4 v[136:139], v[198:199], off offset:256
	v_or_b32_e32 v134, 48, v130
	v_ashrrev_i32_e32 v135, 31, v134
	v_lshlrev_b64 v[134:135], 11, v[134:135]
	v_lshl_add_u64 v[134:135], v[132:133], 0, v[134:135]
	v_lshl_add_u64 v[198:199], v[134:135], 0, v[208:209]
	global_load_dwordx4 v[140:143], v[198:199], off
	global_load_dwordx4 v[180:183], v[198:199], off offset:256
	v_lshl_add_u64 v[166:167], s[26:27], 0, v[166:167]
	v_lshl_add_u64 v[166:167], v[166:167], 0, s[0:1]
	v_lshl_add_u64 v[166:167], v[166:167], 0, v[128:129]
	s_waitcnt vmcnt(0)
	v_permlane16_swap_b32_e32 v168, v170
	v_permlane16_swap_b32_e32 v169, v171
	v_permlane16_swap_b32_e32 v172, v174
	v_permlane16_swap_b32_e32 v173, v175
	v_permlane16_swap_b32_e32 v156, v158
	v_permlane16_swap_b32_e32 v157, v159
	v_permlane16_swap_b32_e32 v152, v154
	v_permlane16_swap_b32_e32 v153, v155
	v_permlane16_swap_b32_e32 v148, v150
	v_permlane16_swap_b32_e32 v149, v151
	v_permlane16_swap_b32_e32 v136, v138
	v_permlane16_swap_b32_e32 v137, v139
	v_permlane16_swap_b32_e32 v140, v142
	v_permlane16_swap_b32_e32 v141, v143
	v_permlane16_swap_b32_e32 v180, v182
	v_permlane16_swap_b32_e32 v181, v183
	v_swap_b32 v156, v158
	v_swap_b32 v157, v159
	v_swap_b32 v152, v154
	v_swap_b32 v153, v155
	v_swap_b32 v148, v150
	v_swap_b32 v149, v151
	v_swap_b32 v138, v142
	v_swap_b32 v139, v143
	v_mov_b32_e32 v146, v136
	v_mov_b32_e32 v147, v137
	v_mov_b32_e32 v136, v180
	v_mov_b32_e32 v137, v181
	v_mov_b32_e32 v134, v182
	v_mov_b32_e32 v135, v183
	v_lshlrev_b32_e32 v128, 16, v168
	v_add_f32_e32 v124, v124, v128
	v_and_b32_e32 v128, 0xffff0000, v168
	v_add_f32_e32 v125, v125, v128
	v_lshlrev_b32_e32 v128, 16, v169
	v_add_f32_e32 v126, v126, v128
	v_and_b32_e32 v128, 0xffff0000, v169
	v_add_f32_e32 v127, v127, v128
	v_mul_f32_e32 v128, v125, v125
	v_lshl_add_u64 v[164:165], v[166:167], 0, v[164:165]
	v_fmac_f32_e32 v128, v124, v124
	v_cvt_pk_bf16_f32 v124, v124, v125
	v_cvt_pk_bf16_f32 v125, v126, v127
	v_mov_b32_e32 v200, v124
	v_mov_b32_e32 v201, v125
	v_lshlrev_b32_e32 v124, 16, v170
	v_add_f32_e32 v116, v116, v124
	v_and_b32_e32 v124, 0xffff0000, v170
	v_add_f32_e32 v117, v117, v124
	v_lshlrev_b32_e32 v124, 16, v171
	v_add_f32_e32 v118, v118, v124
	v_and_b32_e32 v124, 0xffff0000, v171
	v_add_f32_e32 v119, v119, v124
	v_mul_f32_e32 v124, v117, v117
	v_fmac_f32_e32 v124, v116, v116
	v_mul_f32_e32 v125, v119, v119
	v_cvt_pk_bf16_f32 v116, v116, v117
	v_cvt_pk_bf16_f32 v117, v118, v119
	v_and_b32_e32 v119, 0xffff0000, v172
	v_fmac_f32_e32 v125, v118, v118
	v_lshlrev_b32_e32 v118, 16, v172
	v_add_f32_e32 v119, v121, v119
	v_and_b32_e32 v121, 0xffff0000, v173
	v_add_f32_e32 v118, v120, v118
	v_lshlrev_b32_e32 v120, 16, v173
	v_add_f32_e32 v121, v123, v121
	v_mul_f32_e32 v131, v127, v127
	v_add_f32_e32 v120, v122, v120
	v_mul_f32_e32 v122, v119, v119
	v_mul_f32_e32 v123, v121, v121
	v_fmac_f32_e32 v131, v126, v126
	v_fmac_f32_e32 v122, v118, v118
	v_fmac_f32_e32 v123, v120, v120
	v_add_f32_e32 v128, v128, v131
	v_add_f32_e32 v124, v124, v125
	v_add_f32_e32 v122, v122, v123
	v_lshlrev_b32_e32 v123, 16, v174
	v_add_f32_e32 v124, v128, v124
	v_add_f32_e32 v123, v112, v123
	v_and_b32_e32 v112, 0xffff0000, v174
	v_add_f32_e32 v122, v124, v122
	v_add_f32_e32 v124, v113, v112
	v_lshlrev_b32_e32 v112, 16, v175
	v_add_f32_e32 v114, v114, v112
	v_and_b32_e32 v112, 0xffff0000, v175
	v_add_f32_e32 v125, v115, v112
	v_mul_f32_e32 v112, v124, v124
	v_mul_f32_e32 v113, v125, v125
	v_fmac_f32_e32 v112, v123, v123
	v_fmac_f32_e32 v113, v114, v114
	v_add_f32_e32 v112, v112, v113
	v_and_b32_e32 v113, 64, v145
	v_add_f32_e32 v122, v122, v112
	v_xor_b32_e32 v112, 16, v145
	v_add_u32_e32 v126, 64, v113
	v_cmp_lt_i32_e64 s[0:1], v112, v126
	v_mov_b32_e32 v202, v116
	v_mov_b32_e32 v203, v117
	v_bfe_u32 v206, v252, 4, 1
	v_mul_u32_u24_e32 v206, 24, v206
	v_mov_b32_e32 v207, 0
	v_lshl_add_u64 v[204:205], v[164:165], 0, v[206:207]
	v_permlane16_swap_b32_e32 v200, v202
	v_permlane16_swap_b32_e32 v201, v203
	global_store_dwordx4 v[204:205], v[200:203], off
	s_nop 1
	s_nop 0
	v_cndmask_b32_e64 v112, v145, v112, s[0:1]
	v_lshlrev_b32_e32 v115, 2, v112
	v_mov_b32_e32 v127, v122
	s_nop 1
	v_permlane16_swap_b32_e32 v122, v127
	v_cvt_pk_bf16_f32 v112, v118, v119
	v_cvt_pk_bf16_f32 v113, v120, v121
	v_mov_b32_e32 v200, v112
	v_mov_b32_e32 v201, v113
	v_xor_b32_e32 v113, 32, v145
	v_cmp_lt_i32_e64 s[0:1], v113, v126
	s_waitcnt lgkmcnt(0)
	v_add_f32_e32 v112, v122, v127
	v_cvt_pk_bf16_f32 v118, v123, v124
	v_cvt_pk_bf16_f32 v119, v114, v125
	v_lshl_add_u32 v114, v161, 2, v176
	v_cndmask_b32_e64 v113, v145, v113, s[0:1]
	v_lshlrev_b32_e32 v116, 2, v113
	v_mov_b32_e32 v113, v112
	s_nop 1
	v_permlane32_swap_b32_e32 v112, v113
	v_mov_b32_e32 v202, v118
	v_mov_b32_e32 v203, v119
	v_bfe_u32 v206, v252, 4, 1
	v_mul_u32_u24_e32 v206, 24, v206
	v_mov_b32_e32 v207, 0
	v_lshl_add_u64 v[204:205], v[164:165], 0, v[206:207]
	v_permlane16_swap_b32_e32 v200, v202
	v_permlane16_swap_b32_e32 v201, v203
	global_store_dwordx4 v[204:205], v[200:203], off offset:256
	s_nop 1
	s_and_saveexec_b64 s[0:1], vcc
	s_cbranch_execz .LBB0_751
	s_waitcnt lgkmcnt(0)
	v_add_f32_e32 v112, v112, v113
	ds_write_b32 v114, v112
; __device__ __forceinline__ u32x2 pack4(float a, float b, float c, float d) { return u32x2{cvtpk(a, b), cvtpk(c, d)}; }
; __device__ __forceinline__ u32x2 pack4(const f32x4& v) { return u32x2{cvtpk(v[0], v[1]), cvtpk(v[2], v[3])}; }
; #define SBAR() __builtin_amdgcn_sched_barrier(0)
; __global__ void __launch_bounds__(512) fwd_megakernel(Params p) {
;     ...
;         for (int ai = 0; ai < 2; ++ai) { SBAR();
;           u32x2 hv[4][2][2];
;           #pragma unroll
;           for (int m = 0; m < 4; ++m) {
;             const bf16* hr = p_h1b + (long)(brow + ai * 128 + wr * 64 + m * 16 + fr) * DM + pn * 256 + wc * 32 + fq * 4;
;             #pragma unroll
;             for (int bj = 0; bj < 2; ++bj)
;               #pragma unroll
;               for (int n = 0; n < 2; ++n) hv[m][bj][n] = *reinterpret_cast<const u32x2*>(hr + bj * 128 + n * 16);
;           }
;           SBAR();
;           #pragma unroll
;           for (int m = 0; m < 4; ++m) {
;             int lrow = ai * 128 + wr * 64 + m * 16 + fr, row = brow + lrow; float ss = 0.f;
;             bf16* od = p_h2b + (long)row * DM + pn * 256 + wc * 32 + fq * 4;
;             #pragma unroll
;             for (int bj = 0; bj < 2; ++bj)
;               #pragma unroll
;               for (int n = 0; n < 2; ++n) {
;                 const u32x2 hw = hv[m][bj][n];
;                 f32x4 v = acc[ai][bj][m][n];
;                 v[0] += __uint_as_float(hw[0] << 16); v[1] += __uint_as_float(hw[0] & 0xffff0000u);
;                 v[2] += __uint_as_float(hw[1] << 16); v[3] += __uint_as_float(hw[1] & 0xffff0000u);
;                 ss += (v[0] * v[0] + v[1] * v[1]) + (v[2] * v[2] + v[3] * v[3]);
;                 *reinterpret_cast<u32x2*>(od + bj * 128 + n * 16) = pack4(v);
;               }
;             ss += __shfl_xor(ss, 16); ss += __shfl_xor(ss, 32);
;             if (fq == 0) red[wc * 256 + lrow] = ss;
;           }
.LBB0_751:
	s_or_b64 exec, exec, s[0:1]
	v_lshlrev_b32_e32 v117, 5, v162
	v_add3_u32 v112, s29, v161, 16
	s_waitcnt lgkmcnt(0)
	v_ashrrev_i32_e32 v113, 31, v112
	v_lshlrev_b32_e32 v128, 1, v117
	v_lshlrev_b32_e32 v117, 16, v158
	v_lshlrev_b64 v[112:113], 11, v[112:113]
	v_add_f32_e32 v108, v108, v117
	v_and_b32_e32 v117, 0xffff0000, v158
	v_lshl_add_u64 v[112:113], s[26:27], 0, v[112:113]
	v_add_f32_e32 v109, v109, v117
	v_lshlrev_b32_e32 v117, 16, v159
	v_lshlrev_b32_e32 v120, 2, v163
	v_lshl_add_u64 v[112:113], s[30:31], 1, v[112:113]
	v_add_f32_e32 v110, v110, v117
	v_and_b32_e32 v117, 0xffff0000, v159
	v_lshl_add_u64 v[118:119], v[112:113], 0, v[128:129]
	v_lshlrev_b32_e32 v112, 1, v120
	v_mov_b32_e32 v113, v129
	v_add_f32_e32 v111, v111, v117
	v_mul_f32_e32 v117, v109, v109
	v_lshl_add_u64 v[118:119], v[118:119], 0, v[112:113]
	v_fmac_f32_e32 v117, v108, v108
	v_cvt_pk_bf16_f32 v108, v108, v109
	v_cvt_pk_bf16_f32 v109, v110, v111
	v_mov_b32_e32 v200, v108
	v_mov_b32_e32 v201, v109
	v_lshlrev_b32_e32 v108, 16, v156
	v_add_f32_e32 v100, v100, v108
	v_and_b32_e32 v108, 0xffff0000, v156
	v_add_f32_e32 v101, v101, v108
	v_lshlrev_b32_e32 v108, 16, v157
	v_add_f32_e32 v102, v102, v108
	v_and_b32_e32 v108, 0xffff0000, v157
	v_add_f32_e32 v103, v103, v108
	v_mul_f32_e32 v108, v101, v101
	v_fmac_f32_e32 v108, v100, v100
	v_cvt_pk_bf16_f32 v100, v100, v101
	v_lshlrev_b32_e32 v101, 16, v154
	v_add_f32_e32 v104, v104, v101
	v_and_b32_e32 v101, 0xffff0000, v154
	v_add_f32_e32 v105, v105, v101
	v_lshlrev_b32_e32 v101, 16, v155
	v_mul_f32_e32 v109, v103, v103
	v_add_f32_e32 v106, v106, v101
	v_and_b32_e32 v101, 0xffff0000, v155
	v_mul_f32_e32 v120, v111, v111
	v_fmac_f32_e32 v109, v102, v102
	v_add_f32_e32 v107, v107, v101
	v_fmac_f32_e32 v120, v110, v110
	v_add_f32_e32 v108, v108, v109
	v_mul_f32_e32 v101, v105, v105
	v_mul_f32_e32 v109, v107, v107
	v_add_f32_e32 v117, v117, v120
	v_fmac_f32_e32 v101, v104, v104
	v_fmac_f32_e32 v109, v106, v106
	v_add_f32_e32 v108, v117, v108
	v_add_f32_e32 v101, v101, v109
	v_add_f32_e32 v101, v108, v101
	v_lshlrev_b32_e32 v108, 16, v152
	v_add_f32_e32 v108, v96, v108
	v_and_b32_e32 v96, 0xffff0000, v152
	v_add_f32_e32 v109, v97, v96
	v_lshlrev_b32_e32 v96, 16, v153
	v_add_f32_e32 v110, v98, v96
	v_and_b32_e32 v96, 0xffff0000, v153
	v_add_f32_e32 v111, v99, v96
	v_mul_f32_e32 v96, v109, v109
	v_mul_f32_e32 v97, v111, v111
	v_fmac_f32_e32 v96, v108, v108
	v_fmac_f32_e32 v97, v110, v110
	v_add_f32_e32 v96, v96, v97
	v_add_f32_e32 v96, v101, v96
	v_mov_b32_e32 v97, v96
	s_nop 1
	v_permlane16_swap_b32_e32 v96, v97
	v_cvt_pk_bf16_f32 v101, v102, v103
	v_mov_b32_e32 v202, v100
	v_mov_b32_e32 v203, v101
	v_bfe_u32 v206, v252, 4, 1
	v_mul_u32_u24_e32 v206, 24, v206
	v_mov_b32_e32 v207, 0
	v_lshl_add_u64 v[204:205], v[118:119], 0, v[206:207]
	v_permlane16_swap_b32_e32 v200, v202
	v_permlane16_swap_b32_e32 v201, v203
	global_store_dwordx4 v[204:205], v[200:203], off
	s_nop 1
	v_cvt_pk_bf16_f32 v98, v104, v105
	v_cvt_pk_bf16_f32 v99, v106, v107
	s_waitcnt lgkmcnt(0)
	v_add_f32_e32 v96, v96, v97
	v_mov_b32_e32 v97, v96
	s_nop 1
	v_permlane32_swap_b32_e32 v96, v97
	v_mov_b32_e32 v200, v98
	v_mov_b32_e32 v201, v99
	v_cvt_pk_bf16_f32 v98, v108, v109
	v_cvt_pk_bf16_f32 v99, v110, v111
	v_mov_b32_e32 v202, v98
	v_mov_b32_e32 v203, v99
	v_bfe_u32 v206, v252, 4, 1
	v_mul_u32_u24_e32 v206, 24, v206
	v_mov_b32_e32 v207, 0
	v_lshl_add_u64 v[204:205], v[118:119], 0, v[206:207]
	v_permlane16_swap_b32_e32 v200, v202
	v_permlane16_swap_b32_e32 v201, v203
	global_store_dwordx4 v[204:205], v[200:203], off offset:256
	s_nop 1
	s_and_saveexec_b64 s[0:1], vcc
	s_cbranch_execz .LBB0_753
	s_waitcnt lgkmcnt(0)
	v_add_f32_e32 v96, v96, v97
	ds_write_b32 v114, v96 offset:64
.LBB0_753:
	s_or_b64 exec, exec, s[0:1]
	v_add3_u32 v96, s29, v161, 32
	s_waitcnt lgkmcnt(0)
	v_ashrrev_i32_e32 v97, 31, v96
	v_lshlrev_b32_e32 v98, 16, v150
	v_lshlrev_b64 v[96:97], 11, v[96:97]
	v_add_f32_e32 v92, v92, v98
	v_and_b32_e32 v98, 0xffff0000, v150
	v_lshl_add_u64 v[96:97], s[26:27], 0, v[96:97]
	v_add_f32_e32 v93, v93, v98
	v_lshlrev_b32_e32 v98, 16, v151
	v_lshl_add_u64 v[96:97], s[30:31], 1, v[96:97]
	v_add_f32_e32 v94, v94, v98
	v_and_b32_e32 v98, 0xffff0000, v151
	v_lshl_add_u64 v[96:97], v[96:97], 0, v[128:129]
	v_add_f32_e32 v95, v95, v98
	v_mul_f32_e32 v98, v93, v93
	v_lshl_add_u64 v[96:97], v[96:97], 0, v[112:113]
	v_fmac_f32_e32 v98, v92, v92
	v_cvt_pk_bf16_f32 v92, v92, v93
	v_cvt_pk_bf16_f32 v93, v94, v95
	v_mov_b32_e32 v200, v92
	v_mov_b32_e32 v201, v93
	v_lshlrev_b32_e32 v92, 16, v148
	v_add_f32_e32 v84, v84, v92
	v_and_b32_e32 v92, 0xffff0000, v148
	v_add_f32_e32 v85, v85, v92
	v_lshlrev_b32_e32 v92, 16, v149
	v_add_f32_e32 v86, v86, v92
	v_and_b32_e32 v92, 0xffff0000, v149
	v_add_f32_e32 v87, v87, v92
	v_mul_f32_e32 v92, v85, v85
	v_fmac_f32_e32 v92, v84, v84
	v_cvt_pk_bf16_f32 v84, v84, v85
	v_lshlrev_b32_e32 v85, 16, v146
	v_add_f32_e32 v88, v88, v85
	v_and_b32_e32 v85, 0xffff0000, v146
	v_add_f32_e32 v89, v89, v85
	v_lshlrev_b32_e32 v85, 16, v147
	v_mul_f32_e32 v93, v87, v87
	v_add_f32_e32 v90, v90, v85
	v_and_b32_e32 v85, 0xffff0000, v147
	v_mul_f32_e32 v99, v95, v95
	v_fmac_f32_e32 v93, v86, v86
	v_add_f32_e32 v91, v91, v85
	v_fmac_f32_e32 v99, v94, v94
	v_add_f32_e32 v92, v92, v93
	v_mul_f32_e32 v85, v89, v89
	v_mul_f32_e32 v93, v91, v91
	v_add_f32_e32 v98, v98, v99
	v_fmac_f32_e32 v85, v88, v88
	v_fmac_f32_e32 v93, v90, v90
	v_add_f32_e32 v92, v98, v92
	v_add_f32_e32 v85, v85, v93
	v_add_f32_e32 v85, v92, v85
	v_lshlrev_b32_e32 v92, 16, v142
	v_add_f32_e32 v92, v80, v92
	v_and_b32_e32 v80, 0xffff0000, v142
	v_add_f32_e32 v93, v81, v80
	v_lshlrev_b32_e32 v80, 16, v143
	v_add_f32_e32 v94, v82, v80
	v_and_b32_e32 v80, 0xffff0000, v143
	v_add_f32_e32 v95, v83, v80
	v_mul_f32_e32 v80, v93, v93
	v_mul_f32_e32 v81, v95, v95
	v_fmac_f32_e32 v80, v92, v92
	v_fmac_f32_e32 v81, v94, v94
	v_add_f32_e32 v80, v80, v81
	v_add_f32_e32 v80, v85, v80
	v_mov_b32_e32 v81, v80
	s_nop 1
	v_permlane16_swap_b32_e32 v80, v81
	v_cvt_pk_bf16_f32 v85, v86, v87
	v_mov_b32_e32 v202, v84
	v_mov_b32_e32 v203, v85
	v_bfe_u32 v206, v252, 4, 1
	v_mul_u32_u24_e32 v206, 24, v206
	v_mov_b32_e32 v207, 0
	v_lshl_add_u64 v[204:205], v[96:97], 0, v[206:207]
	v_permlane16_swap_b32_e32 v200, v202
	v_permlane16_swap_b32_e32 v201, v203
	global_store_dwordx4 v[204:205], v[200:203], off
	s_nop 1
	v_cvt_pk_bf16_f32 v82, v88, v89
	v_cvt_pk_bf16_f32 v83, v90, v91
	s_waitcnt lgkmcnt(0)
; __device__ __forceinline__ u32x2 pack4(float a, float b, float c, float d) { return u32x2{cvtpk(a, b), cvtpk(c, d)}; }
; __device__ __forceinline__ u32x2 pack4(const f32x4& v) { return u32x2{cvtpk(v[0], v[1]), cvtpk(v[2], v[3])}; }
; #define SBAR() __builtin_amdgcn_sched_barrier(0)
; __global__ void __launch_bounds__(512) fwd_megakernel(Params p) {
;     ...
;         for (int ai = 0; ai < 2; ++ai) { SBAR();
;           u32x2 hv[4][2][2];
;           #pragma unroll
;           for (int m = 0; m < 4; ++m) {
;             const bf16* hr = p_h1b + (long)(brow + ai * 128 + wr * 64 + m * 16 + fr) * DM + pn * 256 + wc * 32 + fq * 4;
;             #pragma unroll
;             for (int bj = 0; bj < 2; ++bj)
;               #pragma unroll
;               for (int n = 0; n < 2; ++n) hv[m][bj][n] = *reinterpret_cast<const u32x2*>(hr + bj * 128 + n * 16);
;           }
;           SBAR();
;           #pragma unroll
;           for (int m = 0; m < 4; ++m) {
;             int lrow = ai * 128 + wr * 64 + m * 16 + fr, row = brow + lrow; float ss = 0.f;
;             bf16* od = p_h2b + (long)row * DM + pn * 256 + wc * 32 + fq * 4;
;             #pragma unroll
;             for (int bj = 0; bj < 2; ++bj)
;               #pragma unroll
;               for (int n = 0; n < 2; ++n) {
;                 const u32x2 hw = hv[m][bj][n];
;                 f32x4 v = acc[ai][bj][m][n];
;                 v[0] += __uint_as_float(hw[0] << 16); v[1] += __uint_as_float(hw[0] & 0xffff0000u);
;                 v[2] += __uint_as_float(hw[1] << 16); v[3] += __uint_as_float(hw[1] & 0xffff0000u);
;                 ss += (v[0] * v[0] + v[1] * v[1]) + (v[2] * v[2] + v[3] * v[3]);
;                 *reinterpret_cast<u32x2*>(od + bj * 128 + n * 16) = pack4(v);
;               }
;             ss += __shfl_xor(ss, 16); ss += __shfl_xor(ss, 32);
;             if (fq == 0) red[wc * 256 + lrow] = ss;
;           }
	v_add_f32_e32 v80, v80, v81
	v_mov_b32_e32 v81, v80
	s_nop 1
	v_permlane32_swap_b32_e32 v80, v81
	v_mov_b32_e32 v200, v82
	v_mov_b32_e32 v201, v83
	v_cvt_pk_bf16_f32 v82, v92, v93
	v_cvt_pk_bf16_f32 v83, v94, v95
	v_mov_b32_e32 v202, v82
	v_mov_b32_e32 v203, v83
	v_bfe_u32 v206, v252, 4, 1
	v_mul_u32_u24_e32 v206, 24, v206
	v_mov_b32_e32 v207, 0
	v_lshl_add_u64 v[204:205], v[96:97], 0, v[206:207]
	v_permlane16_swap_b32_e32 v200, v202
	v_permlane16_swap_b32_e32 v201, v203
	global_store_dwordx4 v[204:205], v[200:203], off offset:256
	s_nop 1
	s_and_saveexec_b64 s[0:1], vcc
	s_cbranch_execz .LBB0_755
	s_waitcnt lgkmcnt(0)
	v_add_f32_e32 v80, v80, v81
	ds_write_b32 v114, v80 offset:128
.LBB0_755:
	s_or_b64 exec, exec, s[0:1]
	v_add3_u32 v80, s29, v161, 48
	s_waitcnt lgkmcnt(0)
	v_ashrrev_i32_e32 v81, 31, v80
	v_lshlrev_b32_e32 v82, 16, v140
	v_lshlrev_b64 v[80:81], 11, v[80:81]
	v_add_f32_e32 v76, v76, v82
	v_and_b32_e32 v82, 0xffff0000, v140
	v_lshl_add_u64 v[80:81], s[26:27], 0, v[80:81]
	v_add_f32_e32 v77, v77, v82
	v_lshlrev_b32_e32 v82, 16, v141
	v_lshl_add_u64 v[80:81], s[30:31], 1, v[80:81]
	v_add_f32_e32 v78, v78, v82
	v_and_b32_e32 v82, 0xffff0000, v141
	v_lshl_add_u64 v[80:81], v[80:81], 0, v[128:129]
	v_mov_b32_e32 v113, v129
	v_add_f32_e32 v79, v79, v82
	v_mul_f32_e32 v82, v77, v77
	v_lshl_add_u64 v[80:81], v[80:81], 0, v[112:113]
	v_fmac_f32_e32 v82, v76, v76
	v_cvt_pk_bf16_f32 v76, v76, v77
	v_cvt_pk_bf16_f32 v77, v78, v79
	v_mov_b32_e32 v200, v76
	v_mov_b32_e32 v201, v77
	v_lshlrev_b32_e32 v76, 16, v138
	v_add_f32_e32 v68, v68, v76
	v_and_b32_e32 v76, 0xffff0000, v138
	v_add_f32_e32 v69, v69, v76
	v_lshlrev_b32_e32 v76, 16, v139
	v_add_f32_e32 v70, v70, v76
	v_and_b32_e32 v76, 0xffff0000, v139
	v_add_f32_e32 v71, v71, v76
	v_mul_f32_e32 v76, v69, v69
	v_fmac_f32_e32 v76, v68, v68
	v_cvt_pk_bf16_f32 v68, v68, v69
	v_lshlrev_b32_e32 v69, 16, v136
	v_add_f32_e32 v72, v72, v69
	v_and_b32_e32 v69, 0xffff0000, v136
	v_add_f32_e32 v73, v73, v69
	v_lshlrev_b32_e32 v69, 16, v137
	v_mul_f32_e32 v77, v71, v71
	v_add_f32_e32 v74, v74, v69
	v_and_b32_e32 v69, 0xffff0000, v137
	v_mul_f32_e32 v83, v79, v79
	v_fmac_f32_e32 v77, v70, v70
	v_add_f32_e32 v75, v75, v69
	v_fmac_f32_e32 v83, v78, v78
	v_add_f32_e32 v76, v76, v77
	v_mul_f32_e32 v69, v73, v73
	v_mul_f32_e32 v77, v75, v75
	v_add_f32_e32 v82, v82, v83
	v_fmac_f32_e32 v69, v72, v72
	v_fmac_f32_e32 v77, v74, v74
	v_add_f32_e32 v76, v82, v76
	v_add_f32_e32 v69, v69, v77
	v_add_f32_e32 v69, v76, v69
	v_lshlrev_b32_e32 v76, 16, v134
	v_add_f32_e32 v76, v64, v76
	v_and_b32_e32 v64, 0xffff0000, v134
	v_add_f32_e32 v77, v65, v64
	v_lshlrev_b32_e32 v64, 16, v135
	v_add_f32_e32 v78, v66, v64
	v_and_b32_e32 v64, 0xffff0000, v135
	v_add_f32_e32 v79, v67, v64
	v_mul_f32_e32 v64, v77, v77
	v_mul_f32_e32 v65, v79, v79
	v_fmac_f32_e32 v64, v76, v76
	v_fmac_f32_e32 v65, v78, v78
	v_add_f32_e32 v64, v64, v65
	v_add_f32_e32 v64, v69, v64
	v_mov_b32_e32 v65, v64
	s_nop 1
	v_permlane16_swap_b32_e32 v64, v65
	v_cvt_pk_bf16_f32 v69, v70, v71
	v_mov_b32_e32 v202, v68
	v_mov_b32_e32 v203, v69
	v_bfe_u32 v206, v252, 4, 1
	v_mul_u32_u24_e32 v206, 24, v206
	v_mov_b32_e32 v207, 0
	v_lshl_add_u64 v[204:205], v[80:81], 0, v[206:207]
	v_permlane16_swap_b32_e32 v200, v202
	v_permlane16_swap_b32_e32 v201, v203
	global_store_dwordx4 v[204:205], v[200:203], off
	s_nop 1
	v_cvt_pk_bf16_f32 v66, v72, v73
	v_cvt_pk_bf16_f32 v67, v74, v75
	s_waitcnt lgkmcnt(0)
	v_add_f32_e32 v64, v64, v65
	v_mov_b32_e32 v65, v64
	s_nop 1
	v_permlane32_swap_b32_e32 v64, v65
	v_mov_b32_e32 v200, v66
	v_mov_b32_e32 v201, v67
	v_cvt_pk_bf16_f32 v66, v76, v77
	v_cvt_pk_bf16_f32 v67, v78, v79
	v_mov_b32_e32 v202, v66
	v_mov_b32_e32 v203, v67
	v_bfe_u32 v206, v252, 4, 1
	v_mul_u32_u24_e32 v206, 24, v206
	v_mov_b32_e32 v207, 0
	v_lshl_add_u64 v[204:205], v[80:81], 0, v[206:207]
	v_permlane16_swap_b32_e32 v200, v202
	v_permlane16_swap_b32_e32 v201, v203
	global_store_dwordx4 v[204:205], v[200:203], off offset:256
	s_nop 1
	s_and_saveexec_b64 s[0:1], vcc
	s_cbranch_execz .LBB0_757
	s_waitcnt lgkmcnt(0)
	v_add_f32_e32 v64, v64, v65
	ds_write_b32 v114, v64 offset:192
.LBB0_757:
	s_or_b64 exec, exec, s[0:1]
	v_add_u32_e32 v64, 0x80, v130
	s_waitcnt lgkmcnt(0)
	v_ashrrev_i32_e32 v65, 31, v64
	v_lshlrev_b64 v[94:95], 11, v[64:65]
	v_lshl_add_u64 v[64:65], v[132:133], 0, v[94:95]
	v_bfe_u32 v208, v252, 4, 1
	v_mul_u32_u24_e32 v208, 24, v208
	v_mov_b32_e32 v209, 0
	v_lshl_add_u64 v[198:199], v[64:65], 0, v[208:209]
	global_load_dwordx4 v[96:99], v[198:199], off
	global_load_dwordx4 v[100:103], v[198:199], off offset:256
	v_add_u32_e32 v64, 0x90, v130
	v_ashrrev_i32_e32 v65, 31, v64
	v_lshlrev_b64 v[92:93], 11, v[64:65]
	v_add_u32_e32 v82, 0xa0, v130
	v_lshl_add_u64 v[64:65], v[132:133], 0, v[92:93]
	v_ashrrev_i32_e32 v83, 31, v82
	v_lshl_add_u64 v[198:199], v[64:65], 0, v[208:209]
	global_load_dwordx4 v[88:91], v[198:199], off
	global_load_dwordx4 v[84:87], v[198:199], off offset:256
	v_lshlrev_b64 v[64:65], 11, v[82:83]
	v_add_u32_e32 v72, 0xb0, v130
	v_lshl_add_u64 v[64:65], v[132:133], 0, v[64:65]
	v_ashrrev_i32_e32 v73, 31, v72
	v_lshl_add_u64 v[198:199], v[64:65], 0, v[208:209]
	global_load_dwordx4 v[180:183], v[198:199], off
	global_load_dwordx4 v[76:79], v[198:199], off offset:256
	v_lshlrev_b64 v[64:65], 11, v[72:73]
	v_lshl_add_u64 v[64:65], v[132:133], 0, v[64:65]
	v_lshl_add_u64 v[198:199], v[64:65], 0, v[208:209]
	global_load_dwordx4 v[68:71], v[198:199], off
	global_load_dwordx4 v[64:67], v[198:199], off offset:256
	s_waitcnt vmcnt(0)
; __device__ __forceinline__ u32x2 pack4(float a, float b, float c, float d) { return u32x2{cvtpk(a, b), cvtpk(c, d)}; }
; __device__ __forceinline__ u32x2 pack4(const f32x4& v) { return u32x2{cvtpk(v[0], v[1]), cvtpk(v[2], v[3])}; }
; #define SBAR() __builtin_amdgcn_sched_barrier(0)
; __global__ void __launch_bounds__(512) fwd_megakernel(Params p) {
;     ...
;         for (int ai = 0; ai < 2; ++ai) { SBAR();
;           u32x2 hv[4][2][2];
;           #pragma unroll
;           for (int m = 0; m < 4; ++m) {
;             const bf16* hr = p_h1b + (long)(brow + ai * 128 + wr * 64 + m * 16 + fr) * DM + pn * 256 + wc * 32 + fq * 4;
;             #pragma unroll
;             for (int bj = 0; bj < 2; ++bj)
;               #pragma unroll
;               for (int n = 0; n < 2; ++n) hv[m][bj][n] = *reinterpret_cast<const u32x2*>(hr + bj * 128 + n * 16);
;           }
;           SBAR();
;           #pragma unroll
;           for (int m = 0; m < 4; ++m) {
;             int lrow = ai * 128 + wr * 64 + m * 16 + fr, row = brow + lrow; float ss = 0.f;
;             bf16* od = p_h2b + (long)row * DM + pn * 256 + wc * 32 + fq * 4;
;             #pragma unroll
;             for (int bj = 0; bj < 2; ++bj)
;               #pragma unroll
;               for (int n = 0; n < 2; ++n) {
;                 const u32x2 hw = hv[m][bj][n];
;                 f32x4 v = acc[ai][bj][m][n];
;                 v[0] += __uint_as_float(hw[0] << 16); v[1] += __uint_as_float(hw[0] & 0xffff0000u);
;                 v[2] += __uint_as_float(hw[1] << 16); v[3] += __uint_as_float(hw[1] & 0xffff0000u);
;                 ss += (v[0] * v[0] + v[1] * v[1]) + (v[2] * v[2] + v[3] * v[3]);
;                 *reinterpret_cast<u32x2*>(od + bj * 128 + n * 16) = pack4(v);
;               }
;             ss += __shfl_xor(ss, 16); ss += __shfl_xor(ss, 32);
;             if (fq == 0) red[wc * 256 + lrow] = ss;
;           }
	v_permlane16_swap_b32_e32 v96, v98
	v_permlane16_swap_b32_e32 v97, v99
	v_permlane16_swap_b32_e32 v100, v102
	v_permlane16_swap_b32_e32 v101, v103
	v_permlane16_swap_b32_e32 v88, v90
	v_permlane16_swap_b32_e32 v89, v91
	v_permlane16_swap_b32_e32 v84, v86
	v_permlane16_swap_b32_e32 v85, v87
	v_permlane16_swap_b32_e32 v180, v182
	v_permlane16_swap_b32_e32 v181, v183
	v_permlane16_swap_b32_e32 v76, v78
	v_permlane16_swap_b32_e32 v77, v79
	v_permlane16_swap_b32_e32 v68, v70
	v_permlane16_swap_b32_e32 v69, v71
	v_permlane16_swap_b32_e32 v64, v66
	v_permlane16_swap_b32_e32 v65, v67
	v_swap_b32 v88, v90
	v_swap_b32 v89, v91
	v_swap_b32 v84, v86
	v_swap_b32 v85, v87
	v_swap_b32 v68, v70
	v_swap_b32 v69, v71
	v_swap_b32 v64, v66
	v_swap_b32 v65, v67
	v_mov_b32_e32 v74, v78
	v_mov_b32_e32 v75, v79
	v_mov_b32_e32 v78, v182
	v_mov_b32_e32 v79, v183
	v_mov_b32_e32 v80, v180
	v_mov_b32_e32 v81, v181
	v_lshlrev_b32_e32 v104, 16, v96
	v_and_b32_e32 v96, 0xffff0000, v96
	v_lshl_add_u64 v[94:95], s[26:27], 0, v[94:95]
	v_add_f32_e32 v61, v61, v96
	v_lshlrev_b32_e32 v96, 16, v97
	v_lshl_add_u64 v[94:95], s[30:31], 1, v[94:95]
	v_add_f32_e32 v62, v62, v96
	v_and_b32_e32 v96, 0xffff0000, v97
	v_lshl_add_u64 v[94:95], v[94:95], 0, v[128:129]
	v_add_f32_e32 v60, v60, v104
	v_add_f32_e32 v63, v63, v96
	v_mul_f32_e32 v96, v61, v61
	v_lshl_add_u64 v[94:95], v[94:95], 0, v[112:113]
	v_fmac_f32_e32 v96, v60, v60
	v_cvt_pk_bf16_f32 v60, v60, v61
	v_cvt_pk_bf16_f32 v61, v62, v63
	v_mov_b32_e32 v200, v60
	v_mov_b32_e32 v201, v61
	s_waitcnt vmcnt(14)
	v_lshlrev_b32_e32 v60, 16, v98
	v_add_f32_e32 v56, v56, v60
	v_and_b32_e32 v60, 0xffff0000, v98
	v_add_f32_e32 v57, v57, v60
	v_lshlrev_b32_e32 v60, 16, v99
	v_add_f32_e32 v58, v58, v60
	v_and_b32_e32 v60, 0xffff0000, v99
	v_add_f32_e32 v59, v59, v60
	v_mul_f32_e32 v60, v57, v57
	v_fmac_f32_e32 v60, v56, v56
	v_cvt_pk_bf16_f32 v56, v56, v57
	s_waitcnt vmcnt(13)
	v_lshlrev_b32_e32 v57, 16, v100
	v_add_f32_e32 v52, v52, v57
	v_and_b32_e32 v57, 0xffff0000, v100
	v_add_f32_e32 v53, v53, v57
	v_lshlrev_b32_e32 v57, 16, v101
	v_mul_f32_e32 v61, v59, v59
	v_add_f32_e32 v54, v54, v57
	v_and_b32_e32 v57, 0xffff0000, v101
	v_mul_f32_e32 v97, v63, v63
	v_fmac_f32_e32 v61, v58, v58
	v_add_f32_e32 v55, v55, v57
	v_fmac_f32_e32 v97, v62, v62
	v_add_f32_e32 v60, v60, v61
	v_mul_f32_e32 v57, v53, v53
	v_mul_f32_e32 v61, v55, v55
	v_add_f32_e32 v96, v96, v97
	v_fmac_f32_e32 v57, v52, v52
	v_fmac_f32_e32 v61, v54, v54
	v_add_f32_e32 v60, v96, v60
	v_add_f32_e32 v57, v57, v61
	v_add_f32_e32 v57, v60, v57
	s_waitcnt vmcnt(12)
	v_lshlrev_b32_e32 v60, 16, v102
	v_add_f32_e32 v60, v48, v60
	v_and_b32_e32 v48, 0xffff0000, v102
	v_add_f32_e32 v61, v49, v48
	v_lshlrev_b32_e32 v48, 16, v103
	v_add_f32_e32 v62, v50, v48
	v_and_b32_e32 v48, 0xffff0000, v103
	v_add_f32_e32 v63, v51, v48
	v_mul_f32_e32 v48, v61, v61
	v_mul_f32_e32 v49, v63, v63
	v_fmac_f32_e32 v48, v60, v60
	v_fmac_f32_e32 v49, v62, v62
	v_add_f32_e32 v48, v48, v49
	v_add_f32_e32 v48, v57, v48
	v_mov_b32_e32 v49, v48
	s_nop 1
	v_permlane16_swap_b32_e32 v48, v49
	v_cvt_pk_bf16_f32 v57, v58, v59
	v_mov_b32_e32 v202, v56
	v_mov_b32_e32 v203, v57
	v_bfe_u32 v206, v252, 4, 1
	v_mul_u32_u24_e32 v206, 24, v206
	v_mov_b32_e32 v207, 0
	v_lshl_add_u64 v[204:205], v[94:95], 0, v[206:207]
	v_permlane16_swap_b32_e32 v200, v202
	v_permlane16_swap_b32_e32 v201, v203
	global_store_dwordx4 v[204:205], v[200:203], off
	s_nop 1
	v_cvt_pk_bf16_f32 v50, v52, v53
	v_cvt_pk_bf16_f32 v51, v54, v55
	s_waitcnt lgkmcnt(0)
	v_add_f32_e32 v48, v48, v49
	v_mov_b32_e32 v49, v48
	s_nop 1
	v_permlane32_swap_b32_e32 v48, v49
	v_mov_b32_e32 v200, v50
	v_mov_b32_e32 v201, v51
	v_cvt_pk_bf16_f32 v50, v60, v61
	v_cvt_pk_bf16_f32 v51, v62, v63
	v_mov_b32_e32 v202, v50
	v_mov_b32_e32 v203, v51
	v_bfe_u32 v206, v252, 4, 1
	v_mul_u32_u24_e32 v206, 24, v206
	v_mov_b32_e32 v207, 0
	v_lshl_add_u64 v[204:205], v[94:95], 0, v[206:207]
	v_permlane16_swap_b32_e32 v200, v202
	v_permlane16_swap_b32_e32 v201, v203
	global_store_dwordx4 v[204:205], v[200:203], off offset:256
	s_nop 1
	s_and_saveexec_b64 s[0:1], vcc
	s_cbranch_execz .LBB0_759
	s_waitcnt lgkmcnt(0)
	v_add_f32_e32 v48, v48, v49
	ds_write_b32 v114, v48 offset:512
.LBB0_759:
	s_or_b64 exec, exec, s[0:1]
	s_waitcnt vmcnt(13)
	v_lshlrev_b32_e32 v50, 16, v90
	v_add_f32_e32 v44, v44, v50
	v_and_b32_e32 v50, 0xffff0000, v90
	s_waitcnt lgkmcnt(0)
	v_lshl_add_u64 v[48:49], s[26:27], 0, v[92:93]
	v_add_f32_e32 v45, v45, v50
	v_lshlrev_b32_e32 v50, 16, v91
	v_lshl_add_u64 v[48:49], s[30:31], 1, v[48:49]
	v_add_f32_e32 v46, v46, v50
	v_and_b32_e32 v50, 0xffff0000, v91
	v_lshl_add_u64 v[48:49], v[48:49], 0, v[128:129]
	v_mov_b32_e32 v113, v129
	v_add_f32_e32 v47, v47, v50
	v_mul_f32_e32 v50, v45, v45
	v_lshl_add_u64 v[48:49], v[48:49], 0, v[112:113]
	v_fmac_f32_e32 v50, v44, v44
	v_cvt_pk_bf16_f32 v44, v44, v45
	v_cvt_pk_bf16_f32 v45, v46, v47
	v_mov_b32_e32 v200, v44
	v_mov_b32_e32 v201, v45
	s_waitcnt vmcnt(12)
	v_lshlrev_b32_e32 v44, 16, v88
	v_add_f32_e32 v40, v40, v44
	v_and_b32_e32 v44, 0xffff0000, v88
	v_add_f32_e32 v41, v41, v44
	v_lshlrev_b32_e32 v44, 16, v89
	v_add_f32_e32 v42, v42, v44
	v_and_b32_e32 v44, 0xffff0000, v89
	v_add_f32_e32 v43, v43, v44
	v_mul_f32_e32 v44, v41, v41
	v_fmac_f32_e32 v44, v40, v40
	v_cvt_pk_bf16_f32 v40, v40, v41
	s_waitcnt vmcnt(11)
; __device__ __forceinline__ u32x2 pack4(float a, float b, float c, float d) { return u32x2{cvtpk(a, b), cvtpk(c, d)}; }
; __device__ __forceinline__ u32x2 pack4(const f32x4& v) { return u32x2{cvtpk(v[0], v[1]), cvtpk(v[2], v[3])}; }
; #define SBAR() __builtin_amdgcn_sched_barrier(0)
; __global__ void __launch_bounds__(512) fwd_megakernel(Params p) {
;     ...
;         for (int ai = 0; ai < 2; ++ai) { SBAR();
;           u32x2 hv[4][2][2];
;           #pragma unroll
;           for (int m = 0; m < 4; ++m) {
;             const bf16* hr = p_h1b + (long)(brow + ai * 128 + wr * 64 + m * 16 + fr) * DM + pn * 256 + wc * 32 + fq * 4;
;             #pragma unroll
;             for (int bj = 0; bj < 2; ++bj)
;               #pragma unroll
;               for (int n = 0; n < 2; ++n) hv[m][bj][n] = *reinterpret_cast<const u32x2*>(hr + bj * 128 + n * 16);
;           }
;           SBAR();
;           #pragma unroll
;           for (int m = 0; m < 4; ++m) {
;             int lrow = ai * 128 + wr * 64 + m * 16 + fr, row = brow + lrow; float ss = 0.f;
;             bf16* od = p_h2b + (long)row * DM + pn * 256 + wc * 32 + fq * 4;
;             #pragma unroll
;             for (int bj = 0; bj < 2; ++bj)
;               #pragma unroll
;               for (int n = 0; n < 2; ++n) {
;                 const u32x2 hw = hv[m][bj][n];
;                 f32x4 v = acc[ai][bj][m][n];
;                 v[0] += __uint_as_float(hw[0] << 16); v[1] += __uint_as_float(hw[0] & 0xffff0000u);
;                 v[2] += __uint_as_float(hw[1] << 16); v[3] += __uint_as_float(hw[1] & 0xffff0000u);
;                 ss += (v[0] * v[0] + v[1] * v[1]) + (v[2] * v[2] + v[3] * v[3]);
;                 *reinterpret_cast<u32x2*>(od + bj * 128 + n * 16) = pack4(v);
;               }
;             ss += __shfl_xor(ss, 16); ss += __shfl_xor(ss, 32);
;             if (fq == 0) red[wc * 256 + lrow] = ss;
;           }
	v_lshlrev_b32_e32 v41, 16, v86
	v_add_f32_e32 v36, v36, v41
	v_and_b32_e32 v41, 0xffff0000, v86
	v_add_f32_e32 v37, v37, v41
	v_lshlrev_b32_e32 v41, 16, v87
	v_mul_f32_e32 v45, v43, v43
	v_add_f32_e32 v38, v38, v41
	v_and_b32_e32 v41, 0xffff0000, v87
	v_mul_f32_e32 v51, v47, v47
	v_fmac_f32_e32 v45, v42, v42
	v_add_f32_e32 v39, v39, v41
	v_fmac_f32_e32 v51, v46, v46
	v_add_f32_e32 v44, v44, v45
	v_mul_f32_e32 v41, v37, v37
	v_mul_f32_e32 v45, v39, v39
	v_add_f32_e32 v50, v50, v51
	v_fmac_f32_e32 v41, v36, v36
	v_fmac_f32_e32 v45, v38, v38
	v_add_f32_e32 v44, v50, v44
	v_add_f32_e32 v41, v41, v45
	v_add_f32_e32 v41, v44, v41
	s_waitcnt vmcnt(10)
	v_lshlrev_b32_e32 v44, 16, v84
	v_add_f32_e32 v44, v32, v44
	v_and_b32_e32 v32, 0xffff0000, v84
	v_add_f32_e32 v45, v33, v32
	v_lshlrev_b32_e32 v32, 16, v85
	v_add_f32_e32 v46, v34, v32
	v_and_b32_e32 v32, 0xffff0000, v85
	v_add_f32_e32 v47, v35, v32
	v_mul_f32_e32 v32, v45, v45
	v_mul_f32_e32 v33, v47, v47
	v_fmac_f32_e32 v32, v44, v44
	v_fmac_f32_e32 v33, v46, v46
	v_add_f32_e32 v32, v32, v33
	v_add_f32_e32 v32, v41, v32
	v_mov_b32_e32 v33, v32
	s_nop 1
	v_permlane16_swap_b32_e32 v32, v33
	v_cvt_pk_bf16_f32 v41, v42, v43
	v_mov_b32_e32 v202, v40
	v_mov_b32_e32 v203, v41
	v_bfe_u32 v206, v252, 4, 1
	v_mul_u32_u24_e32 v206, 24, v206
	v_mov_b32_e32 v207, 0
	v_lshl_add_u64 v[204:205], v[48:49], 0, v[206:207]
	v_permlane16_swap_b32_e32 v200, v202
	v_permlane16_swap_b32_e32 v201, v203
	global_store_dwordx4 v[204:205], v[200:203], off
	s_nop 1
	v_cvt_pk_bf16_f32 v34, v36, v37
	v_cvt_pk_bf16_f32 v35, v38, v39
	s_waitcnt lgkmcnt(0)
	v_add_f32_e32 v32, v32, v33
	v_mov_b32_e32 v33, v32
	s_nop 1
	v_permlane32_swap_b32_e32 v32, v33
	v_mov_b32_e32 v200, v34
	v_mov_b32_e32 v201, v35
	v_cvt_pk_bf16_f32 v34, v44, v45
	v_cvt_pk_bf16_f32 v35, v46, v47
	v_mov_b32_e32 v202, v34
	v_mov_b32_e32 v203, v35
	v_bfe_u32 v206, v252, 4, 1
	v_mul_u32_u24_e32 v206, 24, v206
	v_mov_b32_e32 v207, 0
	v_lshl_add_u64 v[204:205], v[48:49], 0, v[206:207]
	v_permlane16_swap_b32_e32 v200, v202
	v_permlane16_swap_b32_e32 v201, v203
	global_store_dwordx4 v[204:205], v[200:203], off offset:256
	s_nop 1
	s_and_saveexec_b64 s[0:1], vcc
	s_cbranch_execz .LBB0_761
	s_waitcnt lgkmcnt(0)
	v_add_f32_e32 v32, v32, v33
	ds_write_b32 v114, v32 offset:576
.LBB0_761:
	s_or_b64 exec, exec, s[0:1]
	s_waitcnt vmcnt(11)
	v_lshlrev_b32_e32 v34, 16, v80
	s_waitcnt lgkmcnt(0)
	v_lshlrev_b64 v[32:33], 11, v[82:83]
	v_add_f32_e32 v28, v28, v34
	v_and_b32_e32 v34, 0xffff0000, v80
	v_lshl_add_u64 v[32:33], s[26:27], 0, v[32:33]
	v_add_f32_e32 v29, v29, v34
	v_lshlrev_b32_e32 v34, 16, v81
	v_lshl_add_u64 v[32:33], s[30:31], 1, v[32:33]
	v_add_f32_e32 v30, v30, v34
	v_and_b32_e32 v34, 0xffff0000, v81
	v_lshl_add_u64 v[32:33], v[32:33], 0, v[128:129]
	v_add_f32_e32 v31, v31, v34
	v_mul_f32_e32 v34, v29, v29
	v_lshl_add_u64 v[32:33], v[32:33], 0, v[112:113]
	v_fmac_f32_e32 v34, v28, v28
	v_cvt_pk_bf16_f32 v28, v28, v29
	v_cvt_pk_bf16_f32 v29, v30, v31
	v_mov_b32_e32 v200, v28
	v_mov_b32_e32 v201, v29
	s_waitcnt vmcnt(10)
	v_lshlrev_b32_e32 v28, 16, v78
	v_add_f32_e32 v24, v24, v28
	v_and_b32_e32 v28, 0xffff0000, v78
	v_add_f32_e32 v25, v25, v28
	v_lshlrev_b32_e32 v28, 16, v79
	v_add_f32_e32 v26, v26, v28
	v_and_b32_e32 v28, 0xffff0000, v79
	v_add_f32_e32 v27, v27, v28
	v_mul_f32_e32 v28, v25, v25
	v_fmac_f32_e32 v28, v24, v24
	v_cvt_pk_bf16_f32 v24, v24, v25
	s_waitcnt vmcnt(9)
	v_lshlrev_b32_e32 v25, 16, v76
	v_add_f32_e32 v20, v20, v25
	v_and_b32_e32 v25, 0xffff0000, v76
	v_add_f32_e32 v21, v21, v25
	v_lshlrev_b32_e32 v25, 16, v77
	v_mul_f32_e32 v29, v27, v27
	v_add_f32_e32 v22, v22, v25
	v_and_b32_e32 v25, 0xffff0000, v77
	v_mul_f32_e32 v35, v31, v31
	v_fmac_f32_e32 v29, v26, v26
	v_add_f32_e32 v23, v23, v25
	v_fmac_f32_e32 v35, v30, v30
	v_add_f32_e32 v28, v28, v29
	v_mul_f32_e32 v25, v21, v21
	v_mul_f32_e32 v29, v23, v23
	v_add_f32_e32 v34, v34, v35
	v_fmac_f32_e32 v25, v20, v20
	v_fmac_f32_e32 v29, v22, v22
	v_add_f32_e32 v28, v34, v28
	v_add_f32_e32 v25, v25, v29
	v_add_f32_e32 v25, v28, v25
	s_waitcnt vmcnt(8)
	v_lshlrev_b32_e32 v28, 16, v74
	v_add_f32_e32 v28, v16, v28
	v_and_b32_e32 v16, 0xffff0000, v74
	v_add_f32_e32 v29, v17, v16
	v_lshlrev_b32_e32 v16, 16, v75
	v_add_f32_e32 v30, v18, v16
	v_and_b32_e32 v16, 0xffff0000, v75
	v_add_f32_e32 v31, v19, v16
	v_mul_f32_e32 v16, v29, v29
	v_mul_f32_e32 v17, v31, v31
	v_fmac_f32_e32 v16, v28, v28
	v_fmac_f32_e32 v17, v30, v30
	v_add_f32_e32 v16, v16, v17
	v_add_f32_e32 v16, v25, v16
	v_mov_b32_e32 v17, v16
	s_nop 1
	v_permlane16_swap_b32_e32 v16, v17
	v_cvt_pk_bf16_f32 v25, v26, v27
	v_mov_b32_e32 v202, v24
	v_mov_b32_e32 v203, v25
	v_bfe_u32 v206, v252, 4, 1
	v_mul_u32_u24_e32 v206, 24, v206
	v_mov_b32_e32 v207, 0
	v_lshl_add_u64 v[204:205], v[32:33], 0, v[206:207]
	v_permlane16_swap_b32_e32 v200, v202
	v_permlane16_swap_b32_e32 v201, v203
	global_store_dwordx4 v[204:205], v[200:203], off
	s_nop 1
	v_cvt_pk_bf16_f32 v18, v20, v21
	v_cvt_pk_bf16_f32 v19, v22, v23
	s_waitcnt lgkmcnt(0)
	v_add_f32_e32 v16, v16, v17
	v_mov_b32_e32 v17, v16
	s_nop 1
	v_permlane32_swap_b32_e32 v16, v17
	v_mov_b32_e32 v200, v18
	v_mov_b32_e32 v201, v19
	v_cvt_pk_bf16_f32 v18, v28, v29
	v_cvt_pk_bf16_f32 v19, v30, v31
	v_mov_b32_e32 v202, v18
	v_mov_b32_e32 v203, v19
	v_bfe_u32 v206, v252, 4, 1
	v_mul_u32_u24_e32 v206, 24, v206
	v_mov_b32_e32 v207, 0
	v_lshl_add_u64 v[204:205], v[32:33], 0, v[206:207]
	v_permlane16_swap_b32_e32 v200, v202
	v_permlane16_swap_b32_e32 v201, v203
	global_store_dwordx4 v[204:205], v[200:203], off offset:256
	s_nop 1
	s_and_saveexec_b64 s[0:1], vcc
	s_cbranch_execz .LBB0_763
	s_waitcnt lgkmcnt(0)
	v_add_f32_e32 v16, v16, v17
	ds_write_b32 v114, v16 offset:640
; __device__ __forceinline__ u32x2 pack4(float a, float b, float c, float d) { return u32x2{cvtpk(a, b), cvtpk(c, d)}; }
; __device__ __forceinline__ u32x2 pack4(const f32x4& v) { return u32x2{cvtpk(v[0], v[1]), cvtpk(v[2], v[3])}; }
; #define SBAR() __builtin_amdgcn_sched_barrier(0)
; __global__ void __launch_bounds__(512) fwd_megakernel(Params p) {
;     ...
;         for (int ai = 0; ai < 2; ++ai) { SBAR();
;           u32x2 hv[4][2][2];
;           #pragma unroll
;           for (int m = 0; m < 4; ++m) {
;             const bf16* hr = p_h1b + (long)(brow + ai * 128 + wr * 64 + m * 16 + fr) * DM + pn * 256 + wc * 32 + fq * 4;
;             #pragma unroll
;             for (int bj = 0; bj < 2; ++bj)
;               #pragma unroll
;               for (int n = 0; n < 2; ++n) hv[m][bj][n] = *reinterpret_cast<const u32x2*>(hr + bj * 128 + n * 16);
;           }
;           SBAR();
;           #pragma unroll
;           for (int m = 0; m < 4; ++m) {
;             int lrow = ai * 128 + wr * 64 + m * 16 + fr, row = brow + lrow; float ss = 0.f;
;             bf16* od = p_h2b + (long)row * DM + pn * 256 + wc * 32 + fq * 4;
;             #pragma unroll
;             for (int bj = 0; bj < 2; ++bj)
;               #pragma unroll
;               for (int n = 0; n < 2; ++n) {
;                 const u32x2 hw = hv[m][bj][n];
;                 f32x4 v = acc[ai][bj][m][n];
;                 v[0] += __uint_as_float(hw[0] << 16); v[1] += __uint_as_float(hw[0] & 0xffff0000u);
;                 v[2] += __uint_as_float(hw[1] << 16); v[3] += __uint_as_float(hw[1] & 0xffff0000u);
;                 ss += (v[0] * v[0] + v[1] * v[1]) + (v[2] * v[2] + v[3] * v[3]);
;                 *reinterpret_cast<u32x2*>(od + bj * 128 + n * 16) = pack4(v);
;               }
;             ss += __shfl_xor(ss, 16); ss += __shfl_xor(ss, 32);
;             if (fq == 0) red[wc * 256 + lrow] = ss;
;           }
.LBB0_763:
	s_or_b64 exec, exec, s[0:1]
	s_waitcnt vmcnt(9)
	v_lshlrev_b32_e32 v18, 16, v70
	s_waitcnt lgkmcnt(0)
	v_lshlrev_b64 v[16:17], 11, v[72:73]
	v_add_f32_e32 v12, v12, v18
	v_and_b32_e32 v18, 0xffff0000, v70
	v_lshl_add_u64 v[16:17], s[26:27], 0, v[16:17]
	v_add_f32_e32 v13, v13, v18
	v_lshlrev_b32_e32 v18, 16, v71
	v_lshl_add_u64 v[16:17], s[30:31], 1, v[16:17]
	v_add_f32_e32 v14, v14, v18
	v_and_b32_e32 v18, 0xffff0000, v71
	v_lshl_add_u64 v[16:17], v[16:17], 0, v[128:129]
	v_mov_b32_e32 v113, v129
	v_add_f32_e32 v15, v15, v18
	v_mul_f32_e32 v18, v13, v13
	v_lshl_add_u64 v[16:17], v[16:17], 0, v[112:113]
	v_fmac_f32_e32 v18, v12, v12
	v_cvt_pk_bf16_f32 v12, v12, v13
	v_cvt_pk_bf16_f32 v13, v14, v15
	v_mov_b32_e32 v200, v12
	v_mov_b32_e32 v201, v13
	s_waitcnt vmcnt(8)
	v_lshlrev_b32_e32 v12, 16, v68
	v_add_f32_e32 v8, v8, v12
	v_and_b32_e32 v12, 0xffff0000, v68
	v_add_f32_e32 v9, v9, v12
	v_lshlrev_b32_e32 v12, 16, v69
	v_add_f32_e32 v10, v10, v12
	v_and_b32_e32 v12, 0xffff0000, v69
	v_add_f32_e32 v11, v11, v12
	v_mul_f32_e32 v12, v9, v9
	v_fmac_f32_e32 v12, v8, v8
	v_cvt_pk_bf16_f32 v8, v8, v9
	s_waitcnt vmcnt(7)
	v_lshlrev_b32_e32 v9, 16, v66
	v_add_f32_e32 v4, v4, v9
	v_and_b32_e32 v9, 0xffff0000, v66
	v_add_f32_e32 v5, v5, v9
	v_lshlrev_b32_e32 v9, 16, v67
	v_mul_f32_e32 v13, v11, v11
	v_add_f32_e32 v6, v6, v9
	v_and_b32_e32 v9, 0xffff0000, v67
	v_mul_f32_e32 v19, v15, v15
	v_fmac_f32_e32 v13, v10, v10
	v_add_f32_e32 v7, v7, v9
	v_fmac_f32_e32 v19, v14, v14
	v_add_f32_e32 v12, v12, v13
	v_mul_f32_e32 v9, v5, v5
	v_mul_f32_e32 v13, v7, v7
	v_add_f32_e32 v18, v18, v19
	v_fmac_f32_e32 v9, v4, v4
	v_fmac_f32_e32 v13, v6, v6
	v_add_f32_e32 v12, v18, v12
	v_add_f32_e32 v9, v9, v13
	v_add_f32_e32 v9, v12, v9
	s_waitcnt vmcnt(6)
	v_lshlrev_b32_e32 v12, 16, v64
	v_add_f32_e32 v12, v0, v12
	v_and_b32_e32 v0, 0xffff0000, v64
	v_add_f32_e32 v13, v1, v0
	v_lshlrev_b32_e32 v0, 16, v65
	v_add_f32_e32 v14, v2, v0
	v_and_b32_e32 v0, 0xffff0000, v65
	v_add_f32_e32 v15, v3, v0
	v_mul_f32_e32 v0, v13, v13
	v_mul_f32_e32 v1, v15, v15
	v_fmac_f32_e32 v0, v12, v12
	v_fmac_f32_e32 v1, v14, v14
	v_add_f32_e32 v0, v0, v1
	v_add_f32_e32 v0, v9, v0
	v_mov_b32_e32 v1, v0
	s_nop 1
	v_permlane16_swap_b32_e32 v0, v1
	v_cvt_pk_bf16_f32 v9, v10, v11
	v_mov_b32_e32 v202, v8
	v_mov_b32_e32 v203, v9
	v_bfe_u32 v206, v252, 4, 1
	v_mul_u32_u24_e32 v206, 24, v206
	v_mov_b32_e32 v207, 0
	v_lshl_add_u64 v[204:205], v[16:17], 0, v[206:207]
	v_permlane16_swap_b32_e32 v200, v202
	v_permlane16_swap_b32_e32 v201, v203
	global_store_dwordx4 v[204:205], v[200:203], off
	s_nop 1
	v_cvt_pk_bf16_f32 v2, v4, v5
	v_cvt_pk_bf16_f32 v3, v6, v7
	s_waitcnt lgkmcnt(0)
	v_add_f32_e32 v0, v0, v1
	v_mov_b32_e32 v1, v0
	s_nop 1
	v_permlane32_swap_b32_e32 v0, v1
	v_mov_b32_e32 v200, v2
	v_mov_b32_e32 v201, v3
	v_cvt_pk_bf16_f32 v2, v12, v13
	v_cvt_pk_bf16_f32 v3, v14, v15
	v_mov_b32_e32 v202, v2
	v_mov_b32_e32 v203, v3
	v_bfe_u32 v206, v252, 4, 1
	v_mul_u32_u24_e32 v206, 24, v206
	v_mov_b32_e32 v207, 0
	v_lshl_add_u64 v[204:205], v[16:17], 0, v[206:207]
	v_permlane16_swap_b32_e32 v200, v202
	v_permlane16_swap_b32_e32 v201, v203
	global_store_dwordx4 v[204:205], v[200:203], off offset:256
	s_nop 1
	s_and_saveexec_b64 s[0:1], vcc
	s_cbranch_execz .LBB0_765
	s_waitcnt lgkmcnt(0)
	v_add_f32_e32 v0, v0, v1
	ds_write_b32 v114, v0 offset:704
